# EpiResid epilogue row loads hoisted (layer-1 out-proj/FFN-down); gla_pre q/k pair loop fully unrolled with all 32 loads prefetched
# baseline (speedup 1.0000x reference)
; DEVI unsigned pk2(float lo, float hi) { f32x2 v = {lo, hi}; bfv2 b = __builtin_convertvector(v, bfv2); return __builtin_bit_cast(unsigned, b); }
; DEVI float bflo(unsigned u) { return __uint_as_float(u << 16); }
; DEVI float bfhi(unsigned u) { return __uint_as_float(u & 0xffff0000u); }
; DEVI void gla_pre(int sw, const P& p, int item, char* smraw) {
;     ...
; #pragma unroll
;     for (int i = tid; i < 64 * 64; i += 256) {
;       int c = i >> 6, d = (i & 63) * 2;
;       unsigned uq = *(const unsigned*)(z + (size_t)c * LDZ1 + 3072 + h * 128 + d);
;       unsigned uk = *(const unsigned*)(z + (size_t)c * LDZ1 + 3584 + h * 128 + d);
;       float c0 = cum[c * 129 + d], c1 = cum[c * 129 + d + 1];
;       unsigned oq = pk2(bflo(uq) * 0.08838834764831845f * __expf(c0), bfhi(uq) * 0.08838834764831845f * __expf(c1));
;       unsigned ok = pk2(bflo(uk) * __expf(-c0), bfhi(uk) * __expf(-c1));
;       *(unsigned*)(QS + c * 136 + d) = oq;
;       *(unsigned*)(KS + c * 136 + d) = ok;
;       *(unsigned*)(qg + (size_t)c * 128 + d) = oq;
;     }
.LBB0_1471:
	v_ashrrev_i32_e32 v146, 6, v2
	v_mov_b64_e32 v[148:149], s[4:5]
	v_and_b32_e32 v147, 0x7e, v1
	v_mad_i64_i32 v[148:149], s[100:101], v146, s59, v[148:149]
	v_lshlrev_b32_e32 v150, 1, v147
	v_mov_b32_e32 v151, v5
	v_lshl_add_u64 v[148:149], v[148:149], 0, s[48:49]
	v_lshl_add_u64 v[148:149], v[148:149], 0, v[150:151]
	v_add_co_u32_e32 v148, vcc, 0x1000, v148
	s_lshl_b32 s98, s59, 2
	s_mov_b32 s99, 0
	v_addc_co_u32_e32 v149, vcc, 0, v149, vcc
	global_load_dword v152, v[148:149], off offset:2048
	global_load_dword v153, v[148:149], off offset:3072
	v_lshl_add_u64 v[148:149], v[148:149], 0, s[98:99]
	global_load_dword v154, v[148:149], off offset:2048
	global_load_dword v155, v[148:149], off offset:3072
	v_lshl_add_u64 v[148:149], v[148:149], 0, s[98:99]
	global_load_dword v156, v[148:149], off offset:2048
	global_load_dword v157, v[148:149], off offset:3072
	v_lshl_add_u64 v[148:149], v[148:149], 0, s[98:99]
	global_load_dword v158, v[148:149], off offset:2048
	global_load_dword v159, v[148:149], off offset:3072
	v_lshl_add_u64 v[148:149], v[148:149], 0, s[98:99]
	global_load_dword v160, v[148:149], off offset:2048
	global_load_dword v161, v[148:149], off offset:3072
	v_lshl_add_u64 v[148:149], v[148:149], 0, s[98:99]
	global_load_dword v162, v[148:149], off offset:2048
	global_load_dword v163, v[148:149], off offset:3072
	v_lshl_add_u64 v[148:149], v[148:149], 0, s[98:99]
	global_load_dword v164, v[148:149], off offset:2048
	global_load_dword v165, v[148:149], off offset:3072
	v_lshl_add_u64 v[148:149], v[148:149], 0, s[98:99]
	global_load_dword v166, v[148:149], off offset:2048
	global_load_dword v167, v[148:149], off offset:3072
	v_lshl_add_u64 v[148:149], v[148:149], 0, s[98:99]
	global_load_dword v168, v[148:149], off offset:2048
	global_load_dword v169, v[148:149], off offset:3072
	v_lshl_add_u64 v[148:149], v[148:149], 0, s[98:99]
	global_load_dword v170, v[148:149], off offset:2048
	global_load_dword v171, v[148:149], off offset:3072
	v_lshl_add_u64 v[148:149], v[148:149], 0, s[98:99]
	global_load_dword v172, v[148:149], off offset:2048
	global_load_dword v173, v[148:149], off offset:3072
	v_lshl_add_u64 v[148:149], v[148:149], 0, s[98:99]
	global_load_dword v174, v[148:149], off offset:2048
	global_load_dword v175, v[148:149], off offset:3072
	v_lshl_add_u64 v[148:149], v[148:149], 0, s[98:99]
	global_load_dword v176, v[148:149], off offset:2048
	global_load_dword v177, v[148:149], off offset:3072
	v_lshl_add_u64 v[148:149], v[148:149], 0, s[98:99]
	global_load_dword v178, v[148:149], off offset:2048
	global_load_dword v179, v[148:149], off offset:3072
	v_lshl_add_u64 v[148:149], v[148:149], 0, s[98:99]
	global_load_dword v180, v[148:149], off offset:2048
	global_load_dword v181, v[148:149], off offset:3072
	v_lshl_add_u64 v[148:149], v[148:149], 0, s[98:99]
	global_load_dword v182, v[148:149], off offset:2048
	global_load_dword v183, v[148:149], off offset:3072
	v_ashrrev_i32_e32 v6, 6, v2
	v_and_b32_e32 v3, 0x7e, v1
	v_lshlrev_b32_e32 v4, 1, v3
	v_lshlrev_b32_e32 v3, 2, v3
	v_mul_lo_u32 v8, v6, s39
	v_add3_u32 v3, s86, v8, v3
	ds_read2_b32 v[8:9], v3 offset1:1
	s_mov_b32 s74, 0x3db504f3
	v_ashrrev_i32_e32 v7, 31, v6
	s_movk_i32 s6, 0xeff
	s_waitcnt lgkmcnt(0)
	v_mul_f32_e32 v3, 0x3fb8aa3b, v8
	v_exp_f32_e32 v12, v3
	v_mul_f32_e32 v3, 0x3fb8aa3b, v9
	v_exp_f32_e32 v13, v3
	v_mul_f32_e32 v8, 0xbfb8aa3b, v8
	v_mul_f32_e32 v9, 0xbfb8aa3b, v9
	v_exp_f32_e32 v8, v8
	v_exp_f32_e32 v9, v9
	v_add_u32_e32 v1, 0x200, v1
	s_waitcnt vmcnt(31)
	v_lshlrev_b32_e32 v10, 16, v152
	v_and_b32_e32 v11, 0xffff0000, v152
	v_pk_mul_f32 v[10:11], v[10:11], s[74:75] op_sel_hi:[1,0]
	s_nop 0
	v_pk_mul_f32 v[10:11], v[10:11], v[12:13]
	s_nop 0
	v_cvt_pk_bf16_f32 v3, v10, v11
	s_waitcnt vmcnt(30)
	v_lshlrev_b32_e32 v10, 16, v153
	v_and_b32_e32 v11, 0xffff0000, v153
	v_pk_mul_f32 v[8:9], v[8:9], v[10:11]
	s_nop 0
	v_cvt_pk_bf16_f32 v8, v8, v9
	v_mul_lo_u32 v9, v6, s41
	v_lshlrev_b64 v[6:7], 8, v[6:7]
	v_lshl_add_u64 v[6:7], s[14:15], 0, v[6:7]
	v_add3_u32 v9, s86, v9, v4
	v_lshl_add_u64 v[6:7], v[6:7], 0, v[4:5]
	ds_write2st64_b32 v9, v3, v8 offset0:147 offset1:215
	global_store_dword v[6:7], v3, off
	v_add_u32_e32 v3, 0x100, v2
	v_mov_b32_e32 v2, v3
	v_ashrrev_i32_e32 v6, 6, v2
	v_and_b32_e32 v3, 0x7e, v1
	v_lshlrev_b32_e32 v4, 1, v3
	v_lshlrev_b32_e32 v3, 2, v3
	v_mul_lo_u32 v8, v6, s39
	v_add3_u32 v3, s86, v8, v3
	ds_read2_b32 v[8:9], v3 offset1:1
	s_mov_b32 s74, 0x3db504f3
	v_ashrrev_i32_e32 v7, 31, v6
	s_movk_i32 s6, 0xeff
	s_waitcnt lgkmcnt(0)
	v_mul_f32_e32 v3, 0x3fb8aa3b, v8
	v_exp_f32_e32 v12, v3
	v_mul_f32_e32 v3, 0x3fb8aa3b, v9
	v_exp_f32_e32 v13, v3
	v_mul_f32_e32 v8, 0xbfb8aa3b, v8
	v_mul_f32_e32 v9, 0xbfb8aa3b, v9
	v_exp_f32_e32 v8, v8
	v_exp_f32_e32 v9, v9
	v_add_u32_e32 v1, 0x200, v1
	s_waitcnt vmcnt(30)
	v_lshlrev_b32_e32 v10, 16, v154
	v_and_b32_e32 v11, 0xffff0000, v154
	v_pk_mul_f32 v[10:11], v[10:11], s[74:75] op_sel_hi:[1,0]
	s_nop 0
	v_pk_mul_f32 v[10:11], v[10:11], v[12:13]
	s_nop 0
	v_cvt_pk_bf16_f32 v3, v10, v11
	s_waitcnt vmcnt(29)
	v_lshlrev_b32_e32 v10, 16, v155
	v_and_b32_e32 v11, 0xffff0000, v155
	v_pk_mul_f32 v[8:9], v[8:9], v[10:11]
	s_nop 0
	v_cvt_pk_bf16_f32 v8, v8, v9
	v_mul_lo_u32 v9, v6, s41
	v_lshlrev_b64 v[6:7], 8, v[6:7]
	v_lshl_add_u64 v[6:7], s[14:15], 0, v[6:7]
	v_add3_u32 v9, s86, v9, v4
	v_lshl_add_u64 v[6:7], v[6:7], 0, v[4:5]
	ds_write2st64_b32 v9, v3, v8 offset0:147 offset1:215
	global_store_dword v[6:7], v3, off
	v_add_u32_e32 v3, 0x100, v2
	v_mov_b32_e32 v2, v3
	v_ashrrev_i32_e32 v6, 6, v2
	v_and_b32_e32 v3, 0x7e, v1
	v_lshlrev_b32_e32 v4, 1, v3
	v_lshlrev_b32_e32 v3, 2, v3
	v_mul_lo_u32 v8, v6, s39
	v_add3_u32 v3, s86, v8, v3
	ds_read2_b32 v[8:9], v3 offset1:1
	s_mov_b32 s74, 0x3db504f3
	v_ashrrev_i32_e32 v7, 31, v6
	s_movk_i32 s6, 0xeff
	s_waitcnt lgkmcnt(0)
; DEVI unsigned pk2(float lo, float hi) { f32x2 v = {lo, hi}; bfv2 b = __builtin_convertvector(v, bfv2); return __builtin_bit_cast(unsigned, b); }
; DEVI float bflo(unsigned u) { return __uint_as_float(u << 16); }
; DEVI float bfhi(unsigned u) { return __uint_as_float(u & 0xffff0000u); }
; DEVI void gla_pre(int sw, const P& p, int item, char* smraw) {
;     ...
; #pragma unroll
;     for (int i = tid; i < 64 * 64; i += 256) {
;       int c = i >> 6, d = (i & 63) * 2;
;       unsigned uq = *(const unsigned*)(z + (size_t)c * LDZ1 + 3072 + h * 128 + d);
;       unsigned uk = *(const unsigned*)(z + (size_t)c * LDZ1 + 3584 + h * 128 + d);
;       float c0 = cum[c * 129 + d], c1 = cum[c * 129 + d + 1];
;       unsigned oq = pk2(bflo(uq) * 0.08838834764831845f * __expf(c0), bfhi(uq) * 0.08838834764831845f * __expf(c1));
;       unsigned ok = pk2(bflo(uk) * __expf(-c0), bfhi(uk) * __expf(-c1));
;       *(unsigned*)(QS + c * 136 + d) = oq;
;       *(unsigned*)(KS + c * 136 + d) = ok;
;       *(unsigned*)(qg + (size_t)c * 128 + d) = oq;
;     }
	v_mul_f32_e32 v3, 0x3fb8aa3b, v8
	v_exp_f32_e32 v12, v3
	v_mul_f32_e32 v3, 0x3fb8aa3b, v9
	v_exp_f32_e32 v13, v3
	v_mul_f32_e32 v8, 0xbfb8aa3b, v8
	v_mul_f32_e32 v9, 0xbfb8aa3b, v9
	v_exp_f32_e32 v8, v8
	v_exp_f32_e32 v9, v9
	v_add_u32_e32 v1, 0x200, v1
	s_waitcnt vmcnt(29)
	v_lshlrev_b32_e32 v10, 16, v156
	v_and_b32_e32 v11, 0xffff0000, v156
	v_pk_mul_f32 v[10:11], v[10:11], s[74:75] op_sel_hi:[1,0]
	s_nop 0
	v_pk_mul_f32 v[10:11], v[10:11], v[12:13]
	s_nop 0
	v_cvt_pk_bf16_f32 v3, v10, v11
	s_waitcnt vmcnt(28)
	v_lshlrev_b32_e32 v10, 16, v157
	v_and_b32_e32 v11, 0xffff0000, v157
	v_pk_mul_f32 v[8:9], v[8:9], v[10:11]
	s_nop 0
	v_cvt_pk_bf16_f32 v8, v8, v9
	v_mul_lo_u32 v9, v6, s41
	v_lshlrev_b64 v[6:7], 8, v[6:7]
	v_lshl_add_u64 v[6:7], s[14:15], 0, v[6:7]
	v_add3_u32 v9, s86, v9, v4
	v_lshl_add_u64 v[6:7], v[6:7], 0, v[4:5]
	ds_write2st64_b32 v9, v3, v8 offset0:147 offset1:215
	global_store_dword v[6:7], v3, off
	v_add_u32_e32 v3, 0x100, v2
	v_mov_b32_e32 v2, v3
	v_ashrrev_i32_e32 v6, 6, v2
	v_and_b32_e32 v3, 0x7e, v1
	v_lshlrev_b32_e32 v4, 1, v3
	v_lshlrev_b32_e32 v3, 2, v3
	v_mul_lo_u32 v8, v6, s39
	v_add3_u32 v3, s86, v8, v3
	ds_read2_b32 v[8:9], v3 offset1:1
	s_mov_b32 s74, 0x3db504f3
	v_ashrrev_i32_e32 v7, 31, v6
	s_movk_i32 s6, 0xeff
	s_waitcnt lgkmcnt(0)
	v_mul_f32_e32 v3, 0x3fb8aa3b, v8
	v_exp_f32_e32 v12, v3
	v_mul_f32_e32 v3, 0x3fb8aa3b, v9
	v_exp_f32_e32 v13, v3
	v_mul_f32_e32 v8, 0xbfb8aa3b, v8
	v_mul_f32_e32 v9, 0xbfb8aa3b, v9
	v_exp_f32_e32 v8, v8
	v_exp_f32_e32 v9, v9
	v_add_u32_e32 v1, 0x200, v1
	s_waitcnt vmcnt(28)
	v_lshlrev_b32_e32 v10, 16, v158
	v_and_b32_e32 v11, 0xffff0000, v158
	v_pk_mul_f32 v[10:11], v[10:11], s[74:75] op_sel_hi:[1,0]
	s_nop 0
	v_pk_mul_f32 v[10:11], v[10:11], v[12:13]
	s_nop 0
	v_cvt_pk_bf16_f32 v3, v10, v11
	s_waitcnt vmcnt(27)
	v_lshlrev_b32_e32 v10, 16, v159
	v_and_b32_e32 v11, 0xffff0000, v159
	v_pk_mul_f32 v[8:9], v[8:9], v[10:11]
	s_nop 0
	v_cvt_pk_bf16_f32 v8, v8, v9
	v_mul_lo_u32 v9, v6, s41
	v_lshlrev_b64 v[6:7], 8, v[6:7]
	v_lshl_add_u64 v[6:7], s[14:15], 0, v[6:7]
	v_add3_u32 v9, s86, v9, v4
	v_lshl_add_u64 v[6:7], v[6:7], 0, v[4:5]
	ds_write2st64_b32 v9, v3, v8 offset0:147 offset1:215
	global_store_dword v[6:7], v3, off
	v_add_u32_e32 v3, 0x100, v2
	v_mov_b32_e32 v2, v3
	v_ashrrev_i32_e32 v6, 6, v2
	v_and_b32_e32 v3, 0x7e, v1
	v_lshlrev_b32_e32 v4, 1, v3
	v_lshlrev_b32_e32 v3, 2, v3
	v_mul_lo_u32 v8, v6, s39
	v_add3_u32 v3, s86, v8, v3
	ds_read2_b32 v[8:9], v3 offset1:1
	s_mov_b32 s74, 0x3db504f3
	v_ashrrev_i32_e32 v7, 31, v6
	s_movk_i32 s6, 0xeff
	s_waitcnt lgkmcnt(0)
	v_mul_f32_e32 v3, 0x3fb8aa3b, v8
	v_exp_f32_e32 v12, v3
	v_mul_f32_e32 v3, 0x3fb8aa3b, v9
	v_exp_f32_e32 v13, v3
	v_mul_f32_e32 v8, 0xbfb8aa3b, v8
	v_mul_f32_e32 v9, 0xbfb8aa3b, v9
	v_exp_f32_e32 v8, v8
	v_exp_f32_e32 v9, v9
	v_add_u32_e32 v1, 0x200, v1
	s_waitcnt vmcnt(27)
	v_lshlrev_b32_e32 v10, 16, v160
	v_and_b32_e32 v11, 0xffff0000, v160
	v_pk_mul_f32 v[10:11], v[10:11], s[74:75] op_sel_hi:[1,0]
	s_nop 0
	v_pk_mul_f32 v[10:11], v[10:11], v[12:13]
	s_nop 0
	v_cvt_pk_bf16_f32 v3, v10, v11
	s_waitcnt vmcnt(26)
	v_lshlrev_b32_e32 v10, 16, v161
	v_and_b32_e32 v11, 0xffff0000, v161
	v_pk_mul_f32 v[8:9], v[8:9], v[10:11]
	s_nop 0
	v_cvt_pk_bf16_f32 v8, v8, v9
	v_mul_lo_u32 v9, v6, s41
	v_lshlrev_b64 v[6:7], 8, v[6:7]
	v_lshl_add_u64 v[6:7], s[14:15], 0, v[6:7]
	v_add3_u32 v9, s86, v9, v4
	v_lshl_add_u64 v[6:7], v[6:7], 0, v[4:5]
	ds_write2st64_b32 v9, v3, v8 offset0:147 offset1:215
	global_store_dword v[6:7], v3, off
	v_add_u32_e32 v3, 0x100, v2
	v_mov_b32_e32 v2, v3
	v_ashrrev_i32_e32 v6, 6, v2
	v_and_b32_e32 v3, 0x7e, v1
	v_lshlrev_b32_e32 v4, 1, v3
	v_lshlrev_b32_e32 v3, 2, v3
	v_mul_lo_u32 v8, v6, s39
	v_add3_u32 v3, s86, v8, v3
	ds_read2_b32 v[8:9], v3 offset1:1
	s_mov_b32 s74, 0x3db504f3
	v_ashrrev_i32_e32 v7, 31, v6
	s_movk_i32 s6, 0xeff
	s_waitcnt lgkmcnt(0)
	v_mul_f32_e32 v3, 0x3fb8aa3b, v8
	v_exp_f32_e32 v12, v3
	v_mul_f32_e32 v3, 0x3fb8aa3b, v9
	v_exp_f32_e32 v13, v3
	v_mul_f32_e32 v8, 0xbfb8aa3b, v8
	v_mul_f32_e32 v9, 0xbfb8aa3b, v9
	v_exp_f32_e32 v8, v8
	v_exp_f32_e32 v9, v9
	v_add_u32_e32 v1, 0x200, v1
	s_waitcnt vmcnt(26)
	v_lshlrev_b32_e32 v10, 16, v162
	v_and_b32_e32 v11, 0xffff0000, v162
	v_pk_mul_f32 v[10:11], v[10:11], s[74:75] op_sel_hi:[1,0]
	s_nop 0
	v_pk_mul_f32 v[10:11], v[10:11], v[12:13]
	s_nop 0
	v_cvt_pk_bf16_f32 v3, v10, v11
	s_waitcnt vmcnt(25)
	v_lshlrev_b32_e32 v10, 16, v163
	v_and_b32_e32 v11, 0xffff0000, v163
	v_pk_mul_f32 v[8:9], v[8:9], v[10:11]
	s_nop 0
	v_cvt_pk_bf16_f32 v8, v8, v9
	v_mul_lo_u32 v9, v6, s41
	v_lshlrev_b64 v[6:7], 8, v[6:7]
	v_lshl_add_u64 v[6:7], s[14:15], 0, v[6:7]
	v_add3_u32 v9, s86, v9, v4
	v_lshl_add_u64 v[6:7], v[6:7], 0, v[4:5]
	ds_write2st64_b32 v9, v3, v8 offset0:147 offset1:215
	global_store_dword v[6:7], v3, off
	v_add_u32_e32 v3, 0x100, v2
	v_mov_b32_e32 v2, v3
	v_ashrrev_i32_e32 v6, 6, v2
	v_and_b32_e32 v3, 0x7e, v1
	v_lshlrev_b32_e32 v4, 1, v3
	v_lshlrev_b32_e32 v3, 2, v3
	v_mul_lo_u32 v8, v6, s39
	v_add3_u32 v3, s86, v8, v3
	ds_read2_b32 v[8:9], v3 offset1:1
	s_mov_b32 s74, 0x3db504f3
	v_ashrrev_i32_e32 v7, 31, v6
	s_movk_i32 s6, 0xeff
	s_waitcnt lgkmcnt(0)
	v_mul_f32_e32 v3, 0x3fb8aa3b, v8
	v_exp_f32_e32 v12, v3
	v_mul_f32_e32 v3, 0x3fb8aa3b, v9
	v_exp_f32_e32 v13, v3
	v_mul_f32_e32 v8, 0xbfb8aa3b, v8
	v_mul_f32_e32 v9, 0xbfb8aa3b, v9
	v_exp_f32_e32 v8, v8
	v_exp_f32_e32 v9, v9
	v_add_u32_e32 v1, 0x200, v1
	s_waitcnt vmcnt(25)
	v_lshlrev_b32_e32 v10, 16, v164
	v_and_b32_e32 v11, 0xffff0000, v164
	v_pk_mul_f32 v[10:11], v[10:11], s[74:75] op_sel_hi:[1,0]
	s_nop 0
	v_pk_mul_f32 v[10:11], v[10:11], v[12:13]
	s_nop 0
	v_cvt_pk_bf16_f32 v3, v10, v11
	s_waitcnt vmcnt(24)
; DEVI unsigned pk2(float lo, float hi) { f32x2 v = {lo, hi}; bfv2 b = __builtin_convertvector(v, bfv2); return __builtin_bit_cast(unsigned, b); }
; DEVI float bflo(unsigned u) { return __uint_as_float(u << 16); }
; DEVI float bfhi(unsigned u) { return __uint_as_float(u & 0xffff0000u); }
; DEVI void gla_pre(int sw, const P& p, int item, char* smraw) {
;     ...
; #pragma unroll
;     for (int i = tid; i < 64 * 64; i += 256) {
;       int c = i >> 6, d = (i & 63) * 2;
;       unsigned uq = *(const unsigned*)(z + (size_t)c * LDZ1 + 3072 + h * 128 + d);
;       unsigned uk = *(const unsigned*)(z + (size_t)c * LDZ1 + 3584 + h * 128 + d);
;       float c0 = cum[c * 129 + d], c1 = cum[c * 129 + d + 1];
;       unsigned oq = pk2(bflo(uq) * 0.08838834764831845f * __expf(c0), bfhi(uq) * 0.08838834764831845f * __expf(c1));
;       unsigned ok = pk2(bflo(uk) * __expf(-c0), bfhi(uk) * __expf(-c1));
;       *(unsigned*)(QS + c * 136 + d) = oq;
;       *(unsigned*)(KS + c * 136 + d) = ok;
;       *(unsigned*)(qg + (size_t)c * 128 + d) = oq;
;     }
	v_lshlrev_b32_e32 v10, 16, v165
	v_and_b32_e32 v11, 0xffff0000, v165
	v_pk_mul_f32 v[8:9], v[8:9], v[10:11]
	s_nop 0
	v_cvt_pk_bf16_f32 v8, v8, v9
	v_mul_lo_u32 v9, v6, s41
	v_lshlrev_b64 v[6:7], 8, v[6:7]
	v_lshl_add_u64 v[6:7], s[14:15], 0, v[6:7]
	v_add3_u32 v9, s86, v9, v4
	v_lshl_add_u64 v[6:7], v[6:7], 0, v[4:5]
	ds_write2st64_b32 v9, v3, v8 offset0:147 offset1:215
	global_store_dword v[6:7], v3, off
	v_add_u32_e32 v3, 0x100, v2
	v_mov_b32_e32 v2, v3
	v_ashrrev_i32_e32 v6, 6, v2
	v_and_b32_e32 v3, 0x7e, v1
	v_lshlrev_b32_e32 v4, 1, v3
	v_lshlrev_b32_e32 v3, 2, v3
	v_mul_lo_u32 v8, v6, s39
	v_add3_u32 v3, s86, v8, v3
	ds_read2_b32 v[8:9], v3 offset1:1
	s_mov_b32 s74, 0x3db504f3
	v_ashrrev_i32_e32 v7, 31, v6
	s_movk_i32 s6, 0xeff
	s_waitcnt lgkmcnt(0)
	v_mul_f32_e32 v3, 0x3fb8aa3b, v8
	v_exp_f32_e32 v12, v3
	v_mul_f32_e32 v3, 0x3fb8aa3b, v9
	v_exp_f32_e32 v13, v3
	v_mul_f32_e32 v8, 0xbfb8aa3b, v8
	v_mul_f32_e32 v9, 0xbfb8aa3b, v9
	v_exp_f32_e32 v8, v8
	v_exp_f32_e32 v9, v9
	v_add_u32_e32 v1, 0x200, v1
	s_waitcnt vmcnt(24)
	v_lshlrev_b32_e32 v10, 16, v166
	v_and_b32_e32 v11, 0xffff0000, v166
	v_pk_mul_f32 v[10:11], v[10:11], s[74:75] op_sel_hi:[1,0]
	s_nop 0
	v_pk_mul_f32 v[10:11], v[10:11], v[12:13]
	s_nop 0
	v_cvt_pk_bf16_f32 v3, v10, v11
	s_waitcnt vmcnt(23)
	v_lshlrev_b32_e32 v10, 16, v167
	v_and_b32_e32 v11, 0xffff0000, v167
	v_pk_mul_f32 v[8:9], v[8:9], v[10:11]
	s_nop 0
	v_cvt_pk_bf16_f32 v8, v8, v9
	v_mul_lo_u32 v9, v6, s41
	v_lshlrev_b64 v[6:7], 8, v[6:7]
	v_lshl_add_u64 v[6:7], s[14:15], 0, v[6:7]
	v_add3_u32 v9, s86, v9, v4
	v_lshl_add_u64 v[6:7], v[6:7], 0, v[4:5]
	ds_write2st64_b32 v9, v3, v8 offset0:147 offset1:215
	global_store_dword v[6:7], v3, off
	v_add_u32_e32 v3, 0x100, v2
	v_mov_b32_e32 v2, v3
	v_ashrrev_i32_e32 v6, 6, v2
	v_and_b32_e32 v3, 0x7e, v1
	v_lshlrev_b32_e32 v4, 1, v3
	v_lshlrev_b32_e32 v3, 2, v3
	v_mul_lo_u32 v8, v6, s39
	v_add3_u32 v3, s86, v8, v3
	ds_read2_b32 v[8:9], v3 offset1:1
	s_mov_b32 s74, 0x3db504f3
	v_ashrrev_i32_e32 v7, 31, v6
	s_movk_i32 s6, 0xeff
	s_waitcnt lgkmcnt(0)
	v_mul_f32_e32 v3, 0x3fb8aa3b, v8
	v_exp_f32_e32 v12, v3
	v_mul_f32_e32 v3, 0x3fb8aa3b, v9
	v_exp_f32_e32 v13, v3
	v_mul_f32_e32 v8, 0xbfb8aa3b, v8
	v_mul_f32_e32 v9, 0xbfb8aa3b, v9
	v_exp_f32_e32 v8, v8
	v_exp_f32_e32 v9, v9
	v_add_u32_e32 v1, 0x200, v1
	s_waitcnt vmcnt(23)
	v_lshlrev_b32_e32 v10, 16, v168
	v_and_b32_e32 v11, 0xffff0000, v168
	v_pk_mul_f32 v[10:11], v[10:11], s[74:75] op_sel_hi:[1,0]
	s_nop 0
	v_pk_mul_f32 v[10:11], v[10:11], v[12:13]
	s_nop 0
	v_cvt_pk_bf16_f32 v3, v10, v11
	s_waitcnt vmcnt(22)
	v_lshlrev_b32_e32 v10, 16, v169
	v_and_b32_e32 v11, 0xffff0000, v169
	v_pk_mul_f32 v[8:9], v[8:9], v[10:11]
	s_nop 0
	v_cvt_pk_bf16_f32 v8, v8, v9
	v_mul_lo_u32 v9, v6, s41
	v_lshlrev_b64 v[6:7], 8, v[6:7]
	v_lshl_add_u64 v[6:7], s[14:15], 0, v[6:7]
	v_add3_u32 v9, s86, v9, v4
	v_lshl_add_u64 v[6:7], v[6:7], 0, v[4:5]
	ds_write2st64_b32 v9, v3, v8 offset0:147 offset1:215
	global_store_dword v[6:7], v3, off
	v_add_u32_e32 v3, 0x100, v2
	v_mov_b32_e32 v2, v3
	v_ashrrev_i32_e32 v6, 6, v2
	v_and_b32_e32 v3, 0x7e, v1
	v_lshlrev_b32_e32 v4, 1, v3
	v_lshlrev_b32_e32 v3, 2, v3
	v_mul_lo_u32 v8, v6, s39
	v_add3_u32 v3, s86, v8, v3
	ds_read2_b32 v[8:9], v3 offset1:1
	s_mov_b32 s74, 0x3db504f3
	v_ashrrev_i32_e32 v7, 31, v6
	s_movk_i32 s6, 0xeff
	s_waitcnt lgkmcnt(0)
	v_mul_f32_e32 v3, 0x3fb8aa3b, v8
	v_exp_f32_e32 v12, v3
	v_mul_f32_e32 v3, 0x3fb8aa3b, v9
	v_exp_f32_e32 v13, v3
	v_mul_f32_e32 v8, 0xbfb8aa3b, v8
	v_mul_f32_e32 v9, 0xbfb8aa3b, v9
	v_exp_f32_e32 v8, v8
	v_exp_f32_e32 v9, v9
	v_add_u32_e32 v1, 0x200, v1
	s_waitcnt vmcnt(22)
	v_lshlrev_b32_e32 v10, 16, v170
	v_and_b32_e32 v11, 0xffff0000, v170
	v_pk_mul_f32 v[10:11], v[10:11], s[74:75] op_sel_hi:[1,0]
	s_nop 0
	v_pk_mul_f32 v[10:11], v[10:11], v[12:13]
	s_nop 0
	v_cvt_pk_bf16_f32 v3, v10, v11
	s_waitcnt vmcnt(21)
	v_lshlrev_b32_e32 v10, 16, v171
	v_and_b32_e32 v11, 0xffff0000, v171
	v_pk_mul_f32 v[8:9], v[8:9], v[10:11]
	s_nop 0
	v_cvt_pk_bf16_f32 v8, v8, v9
	v_mul_lo_u32 v9, v6, s41
	v_lshlrev_b64 v[6:7], 8, v[6:7]
	v_lshl_add_u64 v[6:7], s[14:15], 0, v[6:7]
	v_add3_u32 v9, s86, v9, v4
	v_lshl_add_u64 v[6:7], v[6:7], 0, v[4:5]
	ds_write2st64_b32 v9, v3, v8 offset0:147 offset1:215
	global_store_dword v[6:7], v3, off
	v_add_u32_e32 v3, 0x100, v2
	v_mov_b32_e32 v2, v3
	v_ashrrev_i32_e32 v6, 6, v2
	v_and_b32_e32 v3, 0x7e, v1
	v_lshlrev_b32_e32 v4, 1, v3
	v_lshlrev_b32_e32 v3, 2, v3
	v_mul_lo_u32 v8, v6, s39
	v_add3_u32 v3, s86, v8, v3
	ds_read2_b32 v[8:9], v3 offset1:1
	s_mov_b32 s74, 0x3db504f3
	v_ashrrev_i32_e32 v7, 31, v6
	s_movk_i32 s6, 0xeff
	s_waitcnt lgkmcnt(0)
	v_mul_f32_e32 v3, 0x3fb8aa3b, v8
	v_exp_f32_e32 v12, v3
	v_mul_f32_e32 v3, 0x3fb8aa3b, v9
	v_exp_f32_e32 v13, v3
	v_mul_f32_e32 v8, 0xbfb8aa3b, v8
	v_mul_f32_e32 v9, 0xbfb8aa3b, v9
	v_exp_f32_e32 v8, v8
	v_exp_f32_e32 v9, v9
	v_add_u32_e32 v1, 0x200, v1
	s_waitcnt vmcnt(21)
	v_lshlrev_b32_e32 v10, 16, v172
	v_and_b32_e32 v11, 0xffff0000, v172
	v_pk_mul_f32 v[10:11], v[10:11], s[74:75] op_sel_hi:[1,0]
	s_nop 0
	v_pk_mul_f32 v[10:11], v[10:11], v[12:13]
	s_nop 0
	v_cvt_pk_bf16_f32 v3, v10, v11
	s_waitcnt vmcnt(20)
	v_lshlrev_b32_e32 v10, 16, v173
	v_and_b32_e32 v11, 0xffff0000, v173
	v_pk_mul_f32 v[8:9], v[8:9], v[10:11]
	s_nop 0
	v_cvt_pk_bf16_f32 v8, v8, v9
	v_mul_lo_u32 v9, v6, s41
	v_lshlrev_b64 v[6:7], 8, v[6:7]
	v_lshl_add_u64 v[6:7], s[14:15], 0, v[6:7]
	v_add3_u32 v9, s86, v9, v4
	v_lshl_add_u64 v[6:7], v[6:7], 0, v[4:5]
	ds_write2st64_b32 v9, v3, v8 offset0:147 offset1:215
	global_store_dword v[6:7], v3, off
	v_add_u32_e32 v3, 0x100, v2
	v_mov_b32_e32 v2, v3
	v_ashrrev_i32_e32 v6, 6, v2
	v_and_b32_e32 v3, 0x7e, v1
	v_lshlrev_b32_e32 v4, 1, v3
	v_lshlrev_b32_e32 v3, 2, v3
	v_mul_lo_u32 v8, v6, s39
	v_add3_u32 v3, s86, v8, v3
	ds_read2_b32 v[8:9], v3 offset1:1
	s_mov_b32 s74, 0x3db504f3
	v_ashrrev_i32_e32 v7, 31, v6
	s_movk_i32 s6, 0xeff
	s_waitcnt lgkmcnt(0)
; DEVI unsigned pk2(float lo, float hi) { f32x2 v = {lo, hi}; bfv2 b = __builtin_convertvector(v, bfv2); return __builtin_bit_cast(unsigned, b); }
; DEVI float bflo(unsigned u) { return __uint_as_float(u << 16); }
; DEVI float bfhi(unsigned u) { return __uint_as_float(u & 0xffff0000u); }
; DEVI void gla_pre(int sw, const P& p, int item, char* smraw) {
;     ...
; #pragma unroll
;     for (int i = tid; i < 64 * 64; i += 256) {
;       int c = i >> 6, d = (i & 63) * 2;
;       unsigned uq = *(const unsigned*)(z + (size_t)c * LDZ1 + 3072 + h * 128 + d);
;       unsigned uk = *(const unsigned*)(z + (size_t)c * LDZ1 + 3584 + h * 128 + d);
;       float c0 = cum[c * 129 + d], c1 = cum[c * 129 + d + 1];
;       unsigned oq = pk2(bflo(uq) * 0.08838834764831845f * __expf(c0), bfhi(uq) * 0.08838834764831845f * __expf(c1));
;       unsigned ok = pk2(bflo(uk) * __expf(-c0), bfhi(uk) * __expf(-c1));
;       *(unsigned*)(QS + c * 136 + d) = oq;
;       *(unsigned*)(KS + c * 136 + d) = ok;
;       *(unsigned*)(qg + (size_t)c * 128 + d) = oq;
;     }
	v_mul_f32_e32 v3, 0x3fb8aa3b, v8
	v_exp_f32_e32 v12, v3
	v_mul_f32_e32 v3, 0x3fb8aa3b, v9
	v_exp_f32_e32 v13, v3
	v_mul_f32_e32 v8, 0xbfb8aa3b, v8
	v_mul_f32_e32 v9, 0xbfb8aa3b, v9
	v_exp_f32_e32 v8, v8
	v_exp_f32_e32 v9, v9
	v_add_u32_e32 v1, 0x200, v1
	s_waitcnt vmcnt(20)
	v_lshlrev_b32_e32 v10, 16, v174
	v_and_b32_e32 v11, 0xffff0000, v174
	v_pk_mul_f32 v[10:11], v[10:11], s[74:75] op_sel_hi:[1,0]
	s_nop 0
	v_pk_mul_f32 v[10:11], v[10:11], v[12:13]
	s_nop 0
	v_cvt_pk_bf16_f32 v3, v10, v11
	s_waitcnt vmcnt(19)
	v_lshlrev_b32_e32 v10, 16, v175
	v_and_b32_e32 v11, 0xffff0000, v175
	v_pk_mul_f32 v[8:9], v[8:9], v[10:11]
	s_nop 0
	v_cvt_pk_bf16_f32 v8, v8, v9
	v_mul_lo_u32 v9, v6, s41
	v_lshlrev_b64 v[6:7], 8, v[6:7]
	v_lshl_add_u64 v[6:7], s[14:15], 0, v[6:7]
	v_add3_u32 v9, s86, v9, v4
	v_lshl_add_u64 v[6:7], v[6:7], 0, v[4:5]
	ds_write2st64_b32 v9, v3, v8 offset0:147 offset1:215
	global_store_dword v[6:7], v3, off
	v_add_u32_e32 v3, 0x100, v2
	v_mov_b32_e32 v2, v3
	v_ashrrev_i32_e32 v6, 6, v2
	v_and_b32_e32 v3, 0x7e, v1
	v_lshlrev_b32_e32 v4, 1, v3
	v_lshlrev_b32_e32 v3, 2, v3
	v_mul_lo_u32 v8, v6, s39
	v_add3_u32 v3, s86, v8, v3
	ds_read2_b32 v[8:9], v3 offset1:1
	s_mov_b32 s74, 0x3db504f3
	v_ashrrev_i32_e32 v7, 31, v6
	s_movk_i32 s6, 0xeff
	s_waitcnt lgkmcnt(0)
	v_mul_f32_e32 v3, 0x3fb8aa3b, v8
	v_exp_f32_e32 v12, v3
	v_mul_f32_e32 v3, 0x3fb8aa3b, v9
	v_exp_f32_e32 v13, v3
	v_mul_f32_e32 v8, 0xbfb8aa3b, v8
	v_mul_f32_e32 v9, 0xbfb8aa3b, v9
	v_exp_f32_e32 v8, v8
	v_exp_f32_e32 v9, v9
	v_add_u32_e32 v1, 0x200, v1
	s_waitcnt vmcnt(19)
	v_lshlrev_b32_e32 v10, 16, v176
	v_and_b32_e32 v11, 0xffff0000, v176
	v_pk_mul_f32 v[10:11], v[10:11], s[74:75] op_sel_hi:[1,0]
	s_nop 0
	v_pk_mul_f32 v[10:11], v[10:11], v[12:13]
	s_nop 0
	v_cvt_pk_bf16_f32 v3, v10, v11
	s_waitcnt vmcnt(18)
	v_lshlrev_b32_e32 v10, 16, v177
	v_and_b32_e32 v11, 0xffff0000, v177
	v_pk_mul_f32 v[8:9], v[8:9], v[10:11]
	s_nop 0
	v_cvt_pk_bf16_f32 v8, v8, v9
	v_mul_lo_u32 v9, v6, s41
	v_lshlrev_b64 v[6:7], 8, v[6:7]
	v_lshl_add_u64 v[6:7], s[14:15], 0, v[6:7]
	v_add3_u32 v9, s86, v9, v4
	v_lshl_add_u64 v[6:7], v[6:7], 0, v[4:5]
	ds_write2st64_b32 v9, v3, v8 offset0:147 offset1:215
	global_store_dword v[6:7], v3, off
	v_add_u32_e32 v3, 0x100, v2
	v_mov_b32_e32 v2, v3
	v_ashrrev_i32_e32 v6, 6, v2
	v_and_b32_e32 v3, 0x7e, v1
	v_lshlrev_b32_e32 v4, 1, v3
	v_lshlrev_b32_e32 v3, 2, v3
	v_mul_lo_u32 v8, v6, s39
	v_add3_u32 v3, s86, v8, v3
	ds_read2_b32 v[8:9], v3 offset1:1
	s_mov_b32 s74, 0x3db504f3
	v_ashrrev_i32_e32 v7, 31, v6
	s_movk_i32 s6, 0xeff
	s_waitcnt lgkmcnt(0)
	v_mul_f32_e32 v3, 0x3fb8aa3b, v8
	v_exp_f32_e32 v12, v3
	v_mul_f32_e32 v3, 0x3fb8aa3b, v9
	v_exp_f32_e32 v13, v3
	v_mul_f32_e32 v8, 0xbfb8aa3b, v8
	v_mul_f32_e32 v9, 0xbfb8aa3b, v9
	v_exp_f32_e32 v8, v8
	v_exp_f32_e32 v9, v9
	v_add_u32_e32 v1, 0x200, v1
	s_waitcnt vmcnt(18)
	v_lshlrev_b32_e32 v10, 16, v178
	v_and_b32_e32 v11, 0xffff0000, v178
	v_pk_mul_f32 v[10:11], v[10:11], s[74:75] op_sel_hi:[1,0]
	s_nop 0
	v_pk_mul_f32 v[10:11], v[10:11], v[12:13]
	s_nop 0
	v_cvt_pk_bf16_f32 v3, v10, v11
	s_waitcnt vmcnt(17)
	v_lshlrev_b32_e32 v10, 16, v179
	v_and_b32_e32 v11, 0xffff0000, v179
	v_pk_mul_f32 v[8:9], v[8:9], v[10:11]
	s_nop 0
	v_cvt_pk_bf16_f32 v8, v8, v9
	v_mul_lo_u32 v9, v6, s41
	v_lshlrev_b64 v[6:7], 8, v[6:7]
	v_lshl_add_u64 v[6:7], s[14:15], 0, v[6:7]
	v_add3_u32 v9, s86, v9, v4
	v_lshl_add_u64 v[6:7], v[6:7], 0, v[4:5]
	ds_write2st64_b32 v9, v3, v8 offset0:147 offset1:215
	global_store_dword v[6:7], v3, off
	v_add_u32_e32 v3, 0x100, v2
	v_mov_b32_e32 v2, v3
	v_ashrrev_i32_e32 v6, 6, v2
	v_and_b32_e32 v3, 0x7e, v1
	v_lshlrev_b32_e32 v4, 1, v3
	v_lshlrev_b32_e32 v3, 2, v3
	v_mul_lo_u32 v8, v6, s39
	v_add3_u32 v3, s86, v8, v3
	ds_read2_b32 v[8:9], v3 offset1:1
	s_mov_b32 s74, 0x3db504f3
	v_ashrrev_i32_e32 v7, 31, v6
	s_movk_i32 s6, 0xeff
	s_waitcnt lgkmcnt(0)
	v_mul_f32_e32 v3, 0x3fb8aa3b, v8
	v_exp_f32_e32 v12, v3
	v_mul_f32_e32 v3, 0x3fb8aa3b, v9
	v_exp_f32_e32 v13, v3
	v_mul_f32_e32 v8, 0xbfb8aa3b, v8
	v_mul_f32_e32 v9, 0xbfb8aa3b, v9
	v_exp_f32_e32 v8, v8
	v_exp_f32_e32 v9, v9
	v_add_u32_e32 v1, 0x200, v1
	s_waitcnt vmcnt(17)
	v_lshlrev_b32_e32 v10, 16, v180
	v_and_b32_e32 v11, 0xffff0000, v180
	v_pk_mul_f32 v[10:11], v[10:11], s[74:75] op_sel_hi:[1,0]
	s_nop 0
	v_pk_mul_f32 v[10:11], v[10:11], v[12:13]
	s_nop 0
	v_cvt_pk_bf16_f32 v3, v10, v11
	s_waitcnt vmcnt(16)
	v_lshlrev_b32_e32 v10, 16, v181
	v_and_b32_e32 v11, 0xffff0000, v181
	v_pk_mul_f32 v[8:9], v[8:9], v[10:11]
	s_nop 0
	v_cvt_pk_bf16_f32 v8, v8, v9
	v_mul_lo_u32 v9, v6, s41
	v_lshlrev_b64 v[6:7], 8, v[6:7]
	v_lshl_add_u64 v[6:7], s[14:15], 0, v[6:7]
	v_add3_u32 v9, s86, v9, v4
	v_lshl_add_u64 v[6:7], v[6:7], 0, v[4:5]
	ds_write2st64_b32 v9, v3, v8 offset0:147 offset1:215
	global_store_dword v[6:7], v3, off
	v_add_u32_e32 v3, 0x100, v2
	v_mov_b32_e32 v2, v3
	v_ashrrev_i32_e32 v6, 6, v2
	v_and_b32_e32 v3, 0x7e, v1
	v_lshlrev_b32_e32 v4, 1, v3
	v_lshlrev_b32_e32 v3, 2, v3
	v_mul_lo_u32 v8, v6, s39
	v_add3_u32 v3, s86, v8, v3
	ds_read2_b32 v[8:9], v3 offset1:1
	s_mov_b32 s74, 0x3db504f3
	v_ashrrev_i32_e32 v7, 31, v6
	s_movk_i32 s6, 0xeff
	s_waitcnt lgkmcnt(0)
	v_mul_f32_e32 v3, 0x3fb8aa3b, v8
	v_exp_f32_e32 v12, v3
	v_mul_f32_e32 v3, 0x3fb8aa3b, v9
	v_exp_f32_e32 v13, v3
	v_mul_f32_e32 v8, 0xbfb8aa3b, v8
	v_mul_f32_e32 v9, 0xbfb8aa3b, v9
	v_exp_f32_e32 v8, v8
	v_exp_f32_e32 v9, v9
	v_add_u32_e32 v1, 0x200, v1
	s_waitcnt vmcnt(16)
	v_lshlrev_b32_e32 v10, 16, v182
	v_and_b32_e32 v11, 0xffff0000, v182
	v_pk_mul_f32 v[10:11], v[10:11], s[74:75] op_sel_hi:[1,0]
	s_nop 0
	v_pk_mul_f32 v[10:11], v[10:11], v[12:13]
	s_nop 0
	v_cvt_pk_bf16_f32 v3, v10, v11
	s_waitcnt vmcnt(15)
	v_lshlrev_b32_e32 v10, 16, v183
	v_and_b32_e32 v11, 0xffff0000, v183
	v_pk_mul_f32 v[8:9], v[8:9], v[10:11]
	s_nop 0
	v_cvt_pk_bf16_f32 v8, v8, v9
	v_mul_lo_u32 v9, v6, s41
	v_lshlrev_b64 v[6:7], 8, v[6:7]
	v_lshl_add_u64 v[6:7], s[14:15], 0, v[6:7]
	v_add3_u32 v9, s86, v9, v4
	v_lshl_add_u64 v[6:7], v[6:7], 0, v[4:5]
	ds_write2st64_b32 v9, v3, v8 offset0:147 offset1:215
	global_store_dword v[6:7], v3, off
	v_add_u32_e32 v3, 0x100, v2
	v_mov_b32_e32 v2, v3

;   DEVI void operator()(const f32x4 (&acc)[8][4], int nb, int mb, int fr, int fq, int pk) const {
;     ...
; #pragma unroll
;       for (int mi = 0; mi < 8; ++mi) {
;         const int n = nb + mi * 16 + fq * 4;
;         const f32x4 gv = *(const f32x4*)(g + n);
;         if (pk >= 0) {
;           *(f32x4*)(part + ((size_t)(pk * (NB * CTX) + bb * CTX + qq)) * D + n) = acc[mi][ni];
;         } else {
;           f32x4 xv = *(f32x4*)(xr + n);
;           xv += gv * acc[mi][ni];
;           *(f32x4*)(xr + n) = xv;
;         }
;         if ((mi & 1) == 1) asm volatile("" ::: "memory");
;       }
.LBB0_1668:
	s_or_b64 exec, exec, s[2:3]
	v_lshl_add_u64 v[34:35], v[34:35], 2, s[6:7]
	v_lshl_add_u64 v[46:47], v[34:35], 0, v[128:129]
	v_lshl_add_u64 v[48:49], v[32:33], 0, v[128:129]
	s_add_i32 s61, s61, s60
	s_and_b64 vcc, exec, s[14:15]
	s_mov_b32 s71, s70
	s_mov_b32 s72, s69
	s_mov_b32 s60, s68
	global_load_dwordx4 v[148:151], v[46:47], off
	global_load_dwordx4 v[152:155], v[48:49], off
	global_load_dwordx4 v[156:159], v[48:49], off offset:64
	global_load_dwordx4 v[160:163], v[46:47], off offset:64
	global_load_dwordx4 v[164:167], v[46:47], off offset:128
	global_load_dwordx4 v[168:171], v[48:49], off offset:128
	global_load_dwordx4 v[172:175], v[48:49], off offset:192
	global_load_dwordx4 v[176:179], v[46:47], off offset:192
	global_load_dwordx4 v[180:183], v[46:47], off offset:256
	global_load_dwordx4 v[184:187], v[48:49], off offset:256
	global_load_dwordx4 v[198:201], v[48:49], off offset:320
	global_load_dwordx4 v[202:205], v[46:47], off offset:320
	global_load_dwordx4 v[206:209], v[46:47], off offset:384
	global_load_dwordx4 v[210:213], v[48:49], off offset:384
	global_load_dwordx4 v[220:223], v[48:49], off offset:448
	global_load_dwordx4 v[224:227], v[46:47], off offset:448
	s_waitcnt vmcnt(14)
	s_nop 1
	v_mov_b32_e32 v34, v148
	v_mov_b32_e32 v35, v149
	v_mov_b32_e32 v36, v150
	v_mov_b32_e32 v37, v151
	v_mov_b32_e32 v38, v152
	v_mov_b32_e32 v39, v153
	v_mov_b32_e32 v40, v154
	v_mov_b32_e32 v41, v155
	v_pk_fma_f32 v[2:3], v[2:3], v[36:37], v[40:41]
	v_pk_fma_f32 v[0:1], v[0:1], v[34:35], v[38:39]
	global_store_dwordx4 v[48:49], v[0:3], off
	s_waitcnt vmcnt(13)
	s_nop 1
	v_mov_b32_e32 v42, v156
	v_mov_b32_e32 v43, v157
	v_mov_b32_e32 v44, v158
	v_mov_b32_e32 v45, v159
	v_mov_b32_e32 v0, v160
	v_mov_b32_e32 v1, v161
	v_mov_b32_e32 v2, v162
	v_mov_b32_e32 v3, v163
	v_pk_fma_f32 v[2:3], v[18:19], v[2:3], v[44:45]
	v_pk_fma_f32 v[0:1], v[16:17], v[0:1], v[42:43]
	global_store_dwordx4 v[48:49], v[0:3], off offset:64
	s_waitcnt vmcnt(12)
	s_nop 1
	v_mov_b32_e32 v0, v164
	v_mov_b32_e32 v1, v165
	v_mov_b32_e32 v2, v166
	v_mov_b32_e32 v3, v167
	v_mov_b32_e32 v16, v168
	v_mov_b32_e32 v17, v169
	v_mov_b32_e32 v18, v170
	v_mov_b32_e32 v19, v171
	v_pk_fma_f32 v[2:3], v[6:7], v[2:3], v[18:19]
	v_pk_fma_f32 v[0:1], v[4:5], v[0:1], v[16:17]
	global_store_dwordx4 v[48:49], v[0:3], off offset:128
	s_waitcnt vmcnt(11)
	s_nop 1
	v_mov_b32_e32 v32, v172
	v_mov_b32_e32 v33, v173
	v_mov_b32_e32 v34, v174
	v_mov_b32_e32 v35, v175
	v_mov_b32_e32 v0, v176
	v_mov_b32_e32 v1, v177
	v_mov_b32_e32 v2, v178
	v_mov_b32_e32 v3, v179
	v_pk_fma_f32 v[2:3], v[26:27], v[2:3], v[34:35]
	v_pk_fma_f32 v[0:1], v[24:25], v[0:1], v[32:33]
	global_store_dwordx4 v[48:49], v[0:3], off offset:192
	s_waitcnt vmcnt(10)
	s_nop 1
	v_mov_b32_e32 v0, v180
	v_mov_b32_e32 v1, v181
	v_mov_b32_e32 v2, v182
	v_mov_b32_e32 v3, v183
	v_mov_b32_e32 v4, v184
	v_mov_b32_e32 v5, v185
	v_mov_b32_e32 v6, v186
	v_mov_b32_e32 v7, v187
	v_pk_fma_f32 v[2:3], v[14:15], v[2:3], v[6:7]
	v_pk_fma_f32 v[0:1], v[12:13], v[0:1], v[4:5]
	global_store_dwordx4 v[48:49], v[0:3], off offset:256
	s_waitcnt vmcnt(9)
	s_nop 1
	v_mov_b32_e32 v16, v198
	v_mov_b32_e32 v17, v199
	v_mov_b32_e32 v18, v200
	v_mov_b32_e32 v19, v201
	v_mov_b32_e32 v0, v202
	v_mov_b32_e32 v1, v203
	v_mov_b32_e32 v2, v204
	v_mov_b32_e32 v3, v205
	v_pk_fma_f32 v[2:3], v[30:31], v[2:3], v[18:19]
	v_pk_fma_f32 v[0:1], v[28:29], v[0:1], v[16:17]
	global_store_dwordx4 v[48:49], v[0:3], off offset:320
	s_waitcnt vmcnt(8)
	s_nop 1
	v_mov_b32_e32 v0, v206
	v_mov_b32_e32 v1, v207
	v_mov_b32_e32 v2, v208
	v_mov_b32_e32 v3, v209
	v_mov_b32_e32 v4, v210
	v_mov_b32_e32 v5, v211
	v_mov_b32_e32 v6, v212
	v_mov_b32_e32 v7, v213
	v_pk_fma_f32 v[2:3], v[22:23], v[2:3], v[6:7]
	v_pk_fma_f32 v[0:1], v[20:21], v[0:1], v[4:5]
	global_store_dwordx4 v[48:49], v[0:3], off offset:384
	s_waitcnt vmcnt(7)
	s_nop 1
	v_mov_b32_e32 v12, v220
	v_mov_b32_e32 v13, v221
	v_mov_b32_e32 v14, v222
	v_mov_b32_e32 v15, v223
	v_mov_b32_e32 v0, v224
	v_mov_b32_e32 v1, v225
	v_mov_b32_e32 v2, v226
	v_mov_b32_e32 v3, v227
	v_pk_fma_f32 v[2:3], v[10:11], v[2:3], v[14:15]
	v_pk_fma_f32 v[0:1], v[8:9], v[0:1], v[12:13]
	global_store_dwordx4 v[48:49], v[0:3], off offset:448
	s_cbranch_vccnz .LBB0_1718

;   DEVI void operator()(const f32x4 (&acc)[8][4], int nb, int mb, int fr, int fq, int pk) const {
;     ...
;     for (int ni = 0; ni < 4; ++ni) {
;       const int m = mb + ni * 16 + fr;
;       int bb = m / TPB, qq = m - bb * TPB;
;       float* xr = qq < CTX ? ctxres + (size_t)(bb * CTX + qq) * D : out + (size_t)(bb * SEQ + qq - CTX) * D;
;       const float* g = gate + (size_t)(qq < CTX ? 4 : bb) * MODN;
; #pragma unroll
;       for (int mi = 0; mi < 8; ++mi) {
;         const int n = nb + mi * 16 + fq * 4;
;         const f32x4 gv = *(const f32x4*)(g + n);
;         if (pk >= 0) {
;           *(f32x4*)(part + ((size_t)(pk * (NB * CTX) + bb * CTX + qq)) * D + n) = acc[mi][ni];
;         } else {
;           f32x4 xv = *(f32x4*)(xr + n);
;           xv += gv * acc[mi][ni];
;           *(f32x4*)(xr + n) = xv;
;         }
;         if ((mi & 1) == 1) asm volatile("" ::: "memory");
;       }
.LBB0_1702:
	v_add_u32_e32 v132, s72, v195
	v_mul_hi_i32 v128, v132, s64
	v_lshrrev_b32_e32 v129, 31, v128
	v_ashrrev_i32_e32 v128, 11, v128
	v_add_u32_e32 v133, v128, v129
	v_mad_i32_i24 v134, v133, s65, v132
	v_cmp_lt_i32_e32 vcc, s59, v134
	s_and_saveexec_b64 s[2:3], vcc
	s_xor_b64 s[2:3], exec, s[2:3]
	v_lshlrev_b32_e32 v128, 12, v133
	v_add3_u32 v128, v128, v134, s66
	v_ashrrev_i32_e32 v129, 31, v128
	v_lshlrev_b64 v[128:129], 13, v[128:129]
	v_lshl_add_u64 v[130:131], s[20:21], 0, v[128:129]
	v_mul_hi_i32_i24_e32 v129, 0x3000, v133
	v_mul_i32_i24_e32 v128, 0x3000, v133
	s_andn2_saveexec_b64 s[2:3], s[2:3]
	v_lshl_add_u32 v128, v133, 8, v134
	v_ashrrev_i32_e32 v129, 31, v128
	v_lshlrev_b64 v[128:129], 13, v[128:129]
	v_lshl_add_u64 v[130:131], s[4:5], 0, v[128:129]
	v_mov_b64_e32 v[128:129], 0xc000
	s_or_b64 exec, exec, s[2:3]
	v_add_u32_e32 v134, s71, v196
	v_ashrrev_i32_e32 v135, 31, v134
	v_lshl_add_u64 v[136:137], v[128:129], 2, s[6:7]
	v_lshlrev_b64 v[128:129], 2, v[134:135]
	v_lshl_add_u64 v[146:147], v[136:137], 0, v[128:129]
	v_lshl_add_u64 v[130:131], v[130:131], 0, v[128:129]
	global_load_dwordx4 v[148:151], v[146:147], off
	global_load_dwordx4 v[152:155], v[130:131], off
	global_load_dwordx4 v[156:159], v[130:131], off offset:64
	global_load_dwordx4 v[160:163], v[146:147], off offset:64
	global_load_dwordx4 v[164:167], v[146:147], off offset:128
	global_load_dwordx4 v[168:171], v[130:131], off offset:128
	global_load_dwordx4 v[172:175], v[130:131], off offset:192
	global_load_dwordx4 v[176:179], v[146:147], off offset:192
	global_load_dwordx4 v[180:183], v[146:147], off offset:256
	global_load_dwordx4 v[184:187], v[130:131], off offset:256
	global_load_dwordx4 v[198:201], v[130:131], off offset:320
	global_load_dwordx4 v[202:205], v[146:147], off offset:320
	global_load_dwordx4 v[206:209], v[146:147], off offset:384
	global_load_dwordx4 v[210:213], v[130:131], off offset:384
	global_load_dwordx4 v[220:223], v[130:131], off offset:448
	global_load_dwordx4 v[224:227], v[146:147], off offset:448
	s_waitcnt vmcnt(14)
	s_nop 1
	v_mov_b32_e32 v134, v148
	v_mov_b32_e32 v135, v149
	v_mov_b32_e32 v136, v150
	v_mov_b32_e32 v137, v151
	v_mov_b32_e32 v138, v152
	v_mov_b32_e32 v139, v153
	v_mov_b32_e32 v140, v154
	v_mov_b32_e32 v141, v155
	v_pk_fma_f32 v[98:99], v[98:99], v[136:137], v[140:141]
	v_pk_fma_f32 v[96:97], v[96:97], v[134:135], v[138:139]
	global_store_dwordx4 v[130:131], v[96:99], off
	s_waitcnt vmcnt(13)
	s_nop 1
	v_mov_b32_e32 v142, v156
	v_mov_b32_e32 v143, v157
	v_mov_b32_e32 v144, v158
	v_mov_b32_e32 v145, v159
	v_mov_b32_e32 v96, v160
	v_mov_b32_e32 v97, v161
	v_mov_b32_e32 v98, v162
	v_mov_b32_e32 v99, v163
	v_pk_fma_f32 v[98:99], v[114:115], v[98:99], v[144:145]
	v_pk_fma_f32 v[96:97], v[112:113], v[96:97], v[142:143]
	global_store_dwordx4 v[130:131], v[96:99], off offset:64
	s_waitcnt vmcnt(12)
	s_nop 1
	v_mov_b32_e32 v96, v164
	v_mov_b32_e32 v97, v165
	v_mov_b32_e32 v98, v166
	v_mov_b32_e32 v99, v167
	v_mov_b32_e32 v112, v168
	v_mov_b32_e32 v113, v169
	v_mov_b32_e32 v114, v170
	v_mov_b32_e32 v115, v171
	v_pk_fma_f32 v[98:99], v[102:103], v[98:99], v[114:115]
	v_pk_fma_f32 v[96:97], v[100:101], v[96:97], v[112:113]
	global_store_dwordx4 v[130:131], v[96:99], off offset:128
	s_waitcnt vmcnt(11)
	s_nop 1
	v_mov_b32_e32 v134, v172
	v_mov_b32_e32 v135, v173
	v_mov_b32_e32 v136, v174
	v_mov_b32_e32 v137, v175
	v_mov_b32_e32 v96, v176
	v_mov_b32_e32 v97, v177
	v_mov_b32_e32 v98, v178
	v_mov_b32_e32 v99, v179
	v_pk_fma_f32 v[98:99], v[122:123], v[98:99], v[136:137]
	v_pk_fma_f32 v[96:97], v[120:121], v[96:97], v[134:135]
	global_store_dwordx4 v[130:131], v[96:99], off offset:192
	s_waitcnt vmcnt(10)
	s_nop 1
	v_mov_b32_e32 v96, v180
	v_mov_b32_e32 v97, v181
	v_mov_b32_e32 v98, v182
	v_mov_b32_e32 v99, v183
	v_mov_b32_e32 v100, v184
	v_mov_b32_e32 v101, v185
	v_mov_b32_e32 v102, v186
	v_mov_b32_e32 v103, v187
	v_pk_fma_f32 v[98:99], v[106:107], v[98:99], v[102:103]
	v_pk_fma_f32 v[96:97], v[104:105], v[96:97], v[100:101]
	global_store_dwordx4 v[130:131], v[96:99], off offset:256
	s_waitcnt vmcnt(9)
	s_nop 1
	v_mov_b32_e32 v112, v198
	v_mov_b32_e32 v113, v199
	v_mov_b32_e32 v114, v200
	v_mov_b32_e32 v115, v201
	v_mov_b32_e32 v96, v202
	v_mov_b32_e32 v97, v203
	v_mov_b32_e32 v98, v204
	v_mov_b32_e32 v99, v205
	v_pk_fma_f32 v[98:99], v[126:127], v[98:99], v[114:115]
	v_pk_fma_f32 v[96:97], v[124:125], v[96:97], v[112:113]
	global_store_dwordx4 v[130:131], v[96:99], off offset:320
	s_waitcnt vmcnt(8)
	s_nop 1
	v_mov_b32_e32 v96, v206
	v_mov_b32_e32 v97, v207
	v_mov_b32_e32 v98, v208
	v_mov_b32_e32 v99, v209
	v_mov_b32_e32 v100, v210
	v_mov_b32_e32 v101, v211
	v_mov_b32_e32 v102, v212
	v_mov_b32_e32 v103, v213
	v_pk_fma_f32 v[98:99], v[118:119], v[98:99], v[102:103]
	v_pk_fma_f32 v[96:97], v[116:117], v[96:97], v[100:101]
	global_store_dwordx4 v[130:131], v[96:99], off offset:384
	v_add_u32_e32 v101, 16, v132
	v_mul_hi_i32 v100, v101, s64
	v_lshrrev_b32_e32 v102, 31, v100
	s_waitcnt vmcnt(7)
;   DEVI void operator()(const f32x4 (&acc)[8][4], int nb, int mb, int fr, int fq, int pk) const {
;     ...
;     for (int ni = 0; ni < 4; ++ni) {
;       const int m = mb + ni * 16 + fr;
;       int bb = m / TPB, qq = m - bb * TPB;
;       float* xr = qq < CTX ? ctxres + (size_t)(bb * CTX + qq) * D : out + (size_t)(bb * SEQ + qq - CTX) * D;
;       const float* g = gate + (size_t)(qq < CTX ? 4 : bb) * MODN;
; #pragma unroll
;       for (int mi = 0; mi < 8; ++mi) {
;         const int n = nb + mi * 16 + fq * 4;
;         const f32x4 gv = *(const f32x4*)(g + n);
;         if (pk >= 0) {
;           *(f32x4*)(part + ((size_t)(pk * (NB * CTX) + bb * CTX + qq)) * D + n) = acc[mi][ni];
;         } else {
;           f32x4 xv = *(f32x4*)(xr + n);
;           xv += gv * acc[mi][ni];
;           *(f32x4*)(xr + n) = xv;
;         }
;         if ((mi & 1) == 1) asm volatile("" ::: "memory");
;       }
	s_nop 1
	v_mov_b32_e32 v104, v220
	v_mov_b32_e32 v105, v221
	v_mov_b32_e32 v106, v222
	v_mov_b32_e32 v107, v223
	v_mov_b32_e32 v96, v224
	v_mov_b32_e32 v97, v225
	v_mov_b32_e32 v98, v226
	v_mov_b32_e32 v99, v227
	v_pk_fma_f32 v[98:99], v[110:111], v[98:99], v[106:107]
	v_pk_fma_f32 v[96:97], v[108:109], v[96:97], v[104:105]
	global_store_dwordx4 v[130:131], v[96:99], off offset:448
	s_nop 1
	v_ashrrev_i32_e32 v96, 11, v100
	v_add_u32_e32 v100, v96, v102
	v_mad_i32_i24 v101, v100, s65, v101
	v_cmp_lt_i32_e32 vcc, s59, v101
	s_and_saveexec_b64 s[2:3], vcc
	s_xor_b64 s[2:3], exec, s[2:3]
	v_lshlrev_b32_e32 v96, 12, v100
	v_add3_u32 v96, v96, v101, s66
	v_ashrrev_i32_e32 v97, 31, v96
	v_lshlrev_b64 v[96:97], 13, v[96:97]
	v_lshl_add_u64 v[96:97], s[20:21], 0, v[96:97]
	v_mul_hi_i32_i24_e32 v99, 0x3000, v100
	v_mul_i32_i24_e32 v98, 0x3000, v100
	s_andn2_saveexec_b64 s[2:3], s[2:3]
	v_lshl_add_u32 v96, v100, 8, v101
	v_ashrrev_i32_e32 v97, 31, v96
	v_lshlrev_b64 v[96:97], 13, v[96:97]
	v_lshl_add_u64 v[96:97], s[4:5], 0, v[96:97]
	v_mov_b64_e32 v[98:99], 0xc000
	s_or_b64 exec, exec, s[2:3]
	v_lshl_add_u64 v[98:99], v[98:99], 2, s[6:7]
	v_lshl_add_u64 v[110:111], v[98:99], 0, v[128:129]
	v_lshl_add_u64 v[112:113], v[96:97], 0, v[128:129]
	global_load_dwordx4 v[148:151], v[110:111], off
	global_load_dwordx4 v[152:155], v[112:113], off
	global_load_dwordx4 v[156:159], v[112:113], off offset:64
	global_load_dwordx4 v[160:163], v[110:111], off offset:64
	global_load_dwordx4 v[164:167], v[110:111], off offset:128
	global_load_dwordx4 v[168:171], v[112:113], off offset:128
	global_load_dwordx4 v[172:175], v[112:113], off offset:192
	global_load_dwordx4 v[176:179], v[110:111], off offset:192
	global_load_dwordx4 v[180:183], v[110:111], off offset:256
	global_load_dwordx4 v[184:187], v[112:113], off offset:256
	global_load_dwordx4 v[198:201], v[112:113], off offset:320
	global_load_dwordx4 v[202:205], v[110:111], off offset:320
	global_load_dwordx4 v[206:209], v[110:111], off offset:384
	global_load_dwordx4 v[210:213], v[112:113], off offset:384
	global_load_dwordx4 v[220:223], v[112:113], off offset:448
	global_load_dwordx4 v[224:227], v[110:111], off offset:448
	s_waitcnt vmcnt(14)
	s_nop 1
	v_mov_b32_e32 v98, v148
	v_mov_b32_e32 v99, v149
	v_mov_b32_e32 v100, v150
	v_mov_b32_e32 v101, v151
	v_mov_b32_e32 v102, v152
	v_mov_b32_e32 v103, v153
	v_mov_b32_e32 v104, v154
	v_mov_b32_e32 v105, v155
	v_pk_fma_f32 v[66:67], v[66:67], v[100:101], v[104:105]
	v_pk_fma_f32 v[64:65], v[64:65], v[98:99], v[102:103]
	global_store_dwordx4 v[112:113], v[64:67], off
	s_waitcnt vmcnt(13)
	s_nop 1
	v_mov_b32_e32 v106, v156
	v_mov_b32_e32 v107, v157
	v_mov_b32_e32 v108, v158
	v_mov_b32_e32 v109, v159
	v_mov_b32_e32 v64, v160
	v_mov_b32_e32 v65, v161
	v_mov_b32_e32 v66, v162
	v_mov_b32_e32 v67, v163
	v_pk_fma_f32 v[66:67], v[82:83], v[66:67], v[108:109]
	v_pk_fma_f32 v[64:65], v[80:81], v[64:65], v[106:107]
	global_store_dwordx4 v[112:113], v[64:67], off offset:64
	s_waitcnt vmcnt(12)
	s_nop 1
	v_mov_b32_e32 v64, v164
	v_mov_b32_e32 v65, v165
	v_mov_b32_e32 v66, v166
	v_mov_b32_e32 v67, v167
	v_mov_b32_e32 v80, v168
	v_mov_b32_e32 v81, v169
	v_mov_b32_e32 v82, v170
	v_mov_b32_e32 v83, v171
	v_pk_fma_f32 v[66:67], v[70:71], v[66:67], v[82:83]
	v_pk_fma_f32 v[64:65], v[68:69], v[64:65], v[80:81]
	global_store_dwordx4 v[112:113], v[64:67], off offset:128
	s_waitcnt vmcnt(11)
	s_nop 1
	v_mov_b32_e32 v96, v172
	v_mov_b32_e32 v97, v173
	v_mov_b32_e32 v98, v174
	v_mov_b32_e32 v99, v175
	v_mov_b32_e32 v64, v176
	v_mov_b32_e32 v65, v177
	v_mov_b32_e32 v66, v178
	v_mov_b32_e32 v67, v179
	v_pk_fma_f32 v[66:67], v[90:91], v[66:67], v[98:99]
	v_pk_fma_f32 v[64:65], v[88:89], v[64:65], v[96:97]
	global_store_dwordx4 v[112:113], v[64:67], off offset:192
	s_waitcnt vmcnt(10)
	s_nop 1
	v_mov_b32_e32 v64, v180
	v_mov_b32_e32 v65, v181
	v_mov_b32_e32 v66, v182
	v_mov_b32_e32 v67, v183
	v_mov_b32_e32 v68, v184
	v_mov_b32_e32 v69, v185
	v_mov_b32_e32 v70, v186
	v_mov_b32_e32 v71, v187
	v_pk_fma_f32 v[66:67], v[74:75], v[66:67], v[70:71]
	v_pk_fma_f32 v[64:65], v[72:73], v[64:65], v[68:69]
	global_store_dwordx4 v[112:113], v[64:67], off offset:256
	s_waitcnt vmcnt(9)
	s_nop 1
	v_mov_b32_e32 v80, v198
	v_mov_b32_e32 v81, v199
	v_mov_b32_e32 v82, v200
	v_mov_b32_e32 v83, v201
	v_mov_b32_e32 v64, v202
	v_mov_b32_e32 v65, v203
	v_mov_b32_e32 v66, v204
	v_mov_b32_e32 v67, v205
	v_pk_fma_f32 v[66:67], v[94:95], v[66:67], v[82:83]
	v_pk_fma_f32 v[64:65], v[92:93], v[64:65], v[80:81]
	global_store_dwordx4 v[112:113], v[64:67], off offset:320
	s_waitcnt vmcnt(8)
	s_nop 1
	v_mov_b32_e32 v64, v206
	v_mov_b32_e32 v65, v207
	v_mov_b32_e32 v66, v208
	v_mov_b32_e32 v67, v209
	v_mov_b32_e32 v68, v210
	v_mov_b32_e32 v69, v211
	v_mov_b32_e32 v70, v212
	v_mov_b32_e32 v71, v213
	v_pk_fma_f32 v[66:67], v[86:87], v[66:67], v[70:71]
	v_pk_fma_f32 v[64:65], v[84:85], v[64:65], v[68:69]
	global_store_dwordx4 v[112:113], v[64:67], off offset:384
	v_add_u32_e32 v69, 32, v132
	v_mul_hi_i32 v68, v69, s64
	v_lshrrev_b32_e32 v70, 31, v68
	s_waitcnt vmcnt(7)
;   DEVI void operator()(const f32x4 (&acc)[8][4], int nb, int mb, int fr, int fq, int pk) const {
;     ...
;     for (int ni = 0; ni < 4; ++ni) {
;       const int m = mb + ni * 16 + fr;
;       int bb = m / TPB, qq = m - bb * TPB;
;       float* xr = qq < CTX ? ctxres + (size_t)(bb * CTX + qq) * D : out + (size_t)(bb * SEQ + qq - CTX) * D;
;       const float* g = gate + (size_t)(qq < CTX ? 4 : bb) * MODN;
; #pragma unroll
;       for (int mi = 0; mi < 8; ++mi) {
;         const int n = nb + mi * 16 + fq * 4;
;         const f32x4 gv = *(const f32x4*)(g + n);
;         if (pk >= 0) {
;           *(f32x4*)(part + ((size_t)(pk * (NB * CTX) + bb * CTX + qq)) * D + n) = acc[mi][ni];
;         } else {
;           f32x4 xv = *(f32x4*)(xr + n);
;           xv += gv * acc[mi][ni];
;           *(f32x4*)(xr + n) = xv;
;         }
;         if ((mi & 1) == 1) asm volatile("" ::: "memory");
;       }
	s_nop 1
	v_mov_b32_e32 v72, v220
	v_mov_b32_e32 v73, v221
	v_mov_b32_e32 v74, v222
	v_mov_b32_e32 v75, v223
	v_mov_b32_e32 v64, v224
	v_mov_b32_e32 v65, v225
	v_mov_b32_e32 v66, v226
	v_mov_b32_e32 v67, v227
	v_pk_fma_f32 v[66:67], v[78:79], v[66:67], v[74:75]
	v_pk_fma_f32 v[64:65], v[76:77], v[64:65], v[72:73]
	global_store_dwordx4 v[112:113], v[64:67], off offset:448
	s_nop 1
	v_ashrrev_i32_e32 v64, 11, v68
	v_add_u32_e32 v68, v64, v70
	v_mad_i32_i24 v69, v68, s65, v69
	v_cmp_lt_i32_e32 vcc, s59, v69
	s_and_saveexec_b64 s[2:3], vcc
	s_xor_b64 s[2:3], exec, s[2:3]
	v_lshlrev_b32_e32 v64, 12, v68
	v_add3_u32 v64, v64, v69, s66
	v_ashrrev_i32_e32 v65, 31, v64
	v_lshlrev_b64 v[64:65], 13, v[64:65]
	v_lshl_add_u64 v[64:65], s[20:21], 0, v[64:65]
	v_mul_hi_i32_i24_e32 v67, 0x3000, v68
	v_mul_i32_i24_e32 v66, 0x3000, v68
	s_andn2_saveexec_b64 s[2:3], s[2:3]
	v_lshl_add_u32 v64, v68, 8, v69
	v_ashrrev_i32_e32 v65, 31, v64
	v_lshlrev_b64 v[64:65], 13, v[64:65]
	v_lshl_add_u64 v[64:65], s[4:5], 0, v[64:65]
	v_mov_b64_e32 v[66:67], 0xc000
	s_or_b64 exec, exec, s[2:3]
	v_lshl_add_u64 v[66:67], v[66:67], 2, s[6:7]
	v_lshl_add_u64 v[78:79], v[66:67], 0, v[128:129]
	v_lshl_add_u64 v[80:81], v[64:65], 0, v[128:129]
	global_load_dwordx4 v[148:151], v[78:79], off
	global_load_dwordx4 v[152:155], v[80:81], off
	global_load_dwordx4 v[156:159], v[80:81], off offset:64
	global_load_dwordx4 v[160:163], v[78:79], off offset:64
	global_load_dwordx4 v[164:167], v[78:79], off offset:128
	global_load_dwordx4 v[168:171], v[80:81], off offset:128
	global_load_dwordx4 v[172:175], v[80:81], off offset:192
	global_load_dwordx4 v[176:179], v[78:79], off offset:192
	global_load_dwordx4 v[180:183], v[78:79], off offset:256
	global_load_dwordx4 v[184:187], v[80:81], off offset:256
	global_load_dwordx4 v[198:201], v[80:81], off offset:320
	global_load_dwordx4 v[202:205], v[78:79], off offset:320
	global_load_dwordx4 v[206:209], v[78:79], off offset:384
	global_load_dwordx4 v[210:213], v[80:81], off offset:384
	global_load_dwordx4 v[220:223], v[80:81], off offset:448
	global_load_dwordx4 v[224:227], v[78:79], off offset:448
	s_waitcnt vmcnt(14)
	s_nop 1
	v_mov_b32_e32 v66, v148
	v_mov_b32_e32 v67, v149
	v_mov_b32_e32 v68, v150
	v_mov_b32_e32 v69, v151
	v_mov_b32_e32 v70, v152
	v_mov_b32_e32 v71, v153
	v_mov_b32_e32 v72, v154
	v_mov_b32_e32 v73, v155
	v_pk_fma_f32 v[34:35], v[34:35], v[68:69], v[72:73]
	v_pk_fma_f32 v[32:33], v[32:33], v[66:67], v[70:71]
	global_store_dwordx4 v[80:81], v[32:35], off
	s_waitcnt vmcnt(13)
	s_nop 1
	v_mov_b32_e32 v74, v156
	v_mov_b32_e32 v75, v157
	v_mov_b32_e32 v76, v158
	v_mov_b32_e32 v77, v159
	v_mov_b32_e32 v32, v160
	v_mov_b32_e32 v33, v161
	v_mov_b32_e32 v34, v162
	v_mov_b32_e32 v35, v163
	v_pk_fma_f32 v[34:35], v[50:51], v[34:35], v[76:77]
	v_pk_fma_f32 v[32:33], v[48:49], v[32:33], v[74:75]
	global_store_dwordx4 v[80:81], v[32:35], off offset:64
	s_waitcnt vmcnt(12)
	s_nop 1
	v_mov_b32_e32 v32, v164
	v_mov_b32_e32 v33, v165
	v_mov_b32_e32 v34, v166
	v_mov_b32_e32 v35, v167
	v_mov_b32_e32 v48, v168
	v_mov_b32_e32 v49, v169
	v_mov_b32_e32 v50, v170
	v_mov_b32_e32 v51, v171
	v_pk_fma_f32 v[34:35], v[38:39], v[34:35], v[50:51]
	v_pk_fma_f32 v[32:33], v[36:37], v[32:33], v[48:49]
	global_store_dwordx4 v[80:81], v[32:35], off offset:128
	s_waitcnt vmcnt(11)
	s_nop 1
	v_mov_b32_e32 v64, v172
	v_mov_b32_e32 v65, v173
	v_mov_b32_e32 v66, v174
	v_mov_b32_e32 v67, v175
	v_mov_b32_e32 v32, v176
	v_mov_b32_e32 v33, v177
	v_mov_b32_e32 v34, v178
	v_mov_b32_e32 v35, v179
	v_pk_fma_f32 v[34:35], v[58:59], v[34:35], v[66:67]
	v_pk_fma_f32 v[32:33], v[56:57], v[32:33], v[64:65]
	global_store_dwordx4 v[80:81], v[32:35], off offset:192
	s_waitcnt vmcnt(10)
	s_nop 1
	v_mov_b32_e32 v32, v180
	v_mov_b32_e32 v33, v181
	v_mov_b32_e32 v34, v182
	v_mov_b32_e32 v35, v183
	v_mov_b32_e32 v36, v184
	v_mov_b32_e32 v37, v185
	v_mov_b32_e32 v38, v186
	v_mov_b32_e32 v39, v187
	v_pk_fma_f32 v[34:35], v[42:43], v[34:35], v[38:39]
	v_pk_fma_f32 v[32:33], v[40:41], v[32:33], v[36:37]
	global_store_dwordx4 v[80:81], v[32:35], off offset:256
	s_waitcnt vmcnt(9)
	s_nop 1
	v_mov_b32_e32 v48, v198
	v_mov_b32_e32 v49, v199
	v_mov_b32_e32 v50, v200
	v_mov_b32_e32 v51, v201
	v_mov_b32_e32 v32, v202
	v_mov_b32_e32 v33, v203
	v_mov_b32_e32 v34, v204
	v_mov_b32_e32 v35, v205
	v_pk_fma_f32 v[34:35], v[62:63], v[34:35], v[50:51]
	v_pk_fma_f32 v[32:33], v[60:61], v[32:33], v[48:49]
	global_store_dwordx4 v[80:81], v[32:35], off offset:320
	s_waitcnt vmcnt(8)
	s_nop 1
	v_mov_b32_e32 v32, v206
	v_mov_b32_e32 v33, v207
	v_mov_b32_e32 v34, v208
	v_mov_b32_e32 v35, v209
	v_mov_b32_e32 v36, v210
	v_mov_b32_e32 v37, v211
	v_mov_b32_e32 v38, v212
	v_mov_b32_e32 v39, v213
	v_pk_fma_f32 v[34:35], v[54:55], v[34:35], v[38:39]
	v_pk_fma_f32 v[32:33], v[52:53], v[32:33], v[36:37]
	global_store_dwordx4 v[80:81], v[32:35], off offset:384
	v_add_u32_e32 v37, 48, v132
	v_mul_hi_i32 v36, v37, s64
	v_lshrrev_b32_e32 v38, 31, v36
	s_waitcnt vmcnt(7)
	s_nop 1
	v_mov_b32_e32 v40, v220
	v_mov_b32_e32 v41, v221
	v_mov_b32_e32 v42, v222
	v_mov_b32_e32 v43, v223
	v_mov_b32_e32 v32, v224
	v_mov_b32_e32 v33, v225
	v_mov_b32_e32 v34, v226
	v_mov_b32_e32 v35, v227
	v_pk_fma_f32 v[34:35], v[46:47], v[34:35], v[42:43]
	v_pk_fma_f32 v[32:33], v[44:45], v[32:33], v[40:41]
	global_store_dwordx4 v[80:81], v[32:35], off offset:448
	s_nop 1
	v_ashrrev_i32_e32 v32, 11, v36
	v_add_u32_e32 v36, v32, v38
	v_mad_i32_i24 v37, v36, s65, v37
	v_cmp_lt_i32_e32 vcc, s59, v37
	s_and_saveexec_b64 s[2:3], vcc
	s_xor_b64 s[2:3], exec, s[2:3]
	v_lshlrev_b32_e32 v32, 12, v36
	v_add3_u32 v32, v32, v37, s66
	v_ashrrev_i32_e32 v33, 31, v32
	v_lshlrev_b64 v[32:33], 13, v[32:33]
	v_lshl_add_u64 v[32:33], s[20:21], 0, v[32:33]
	v_mul_hi_i32_i24_e32 v35, 0x3000, v36
	v_mul_i32_i24_e32 v34, 0x3000, v36
	s_andn2_saveexec_b64 s[2:3], s[2:3]
	s_cbranch_execz .LBB0_1668
	v_lshl_add_u32 v32, v36, 8, v37
	v_ashrrev_i32_e32 v33, 31, v32
	v_lshlrev_b64 v[32:33], 13, v[32:33]
	v_lshl_add_u64 v[32:33], s[4:5], 0, v[32:33]
	v_mov_b64_e32 v[34:35], 0xc000
	s_branch .LBB0_1668

;   DEVI void operator()(const f32x4 (&acc)[8][4], int nb, int mb, int fr, int fq, int pk) const {
;     ...
; #pragma unroll
;       for (int mi = 0; mi < 8; ++mi) {
;         const int n = nb + mi * 16 + fq * 4;
;         const f32x4 gv = *(const f32x4*)(g + n);
;         if (pk >= 0) {
;           *(f32x4*)(part + ((size_t)(pk * (NB * CTX) + bb * CTX + qq)) * D + n) = acc[mi][ni];
;         } else {
;           f32x4 xv = *(f32x4*)(xr + n);
;           xv += gv * acc[mi][ni];
;           *(f32x4*)(xr + n) = xv;
;         }
;         if ((mi & 1) == 1) asm volatile("" ::: "memory");
;       }
.LBB0_1791:
	s_or_b64 exec, exec, s[2:3]
	v_lshl_add_u64 v[34:35], v[34:35], 2, s[6:7]
	v_lshl_add_u64 v[46:47], v[34:35], 0, v[128:129]
	v_lshl_add_u64 v[48:49], v[32:33], 0, v[128:129]
	s_add_i32 s52, s52, s58
	s_and_b64 vcc, exec, s[14:15]
	s_mov_b32 s62, s61
	s_mov_b32 s63, s60
	s_mov_b32 s58, s59
	global_load_dwordx4 v[148:151], v[46:47], off
	global_load_dwordx4 v[152:155], v[48:49], off
	global_load_dwordx4 v[156:159], v[48:49], off offset:64
	global_load_dwordx4 v[160:163], v[46:47], off offset:64
	global_load_dwordx4 v[164:167], v[46:47], off offset:128
	global_load_dwordx4 v[168:171], v[48:49], off offset:128
	global_load_dwordx4 v[172:175], v[48:49], off offset:192
	global_load_dwordx4 v[176:179], v[46:47], off offset:192
	global_load_dwordx4 v[180:183], v[46:47], off offset:256
	global_load_dwordx4 v[184:187], v[48:49], off offset:256
	global_load_dwordx4 v[198:201], v[48:49], off offset:320
	global_load_dwordx4 v[202:205], v[46:47], off offset:320
	global_load_dwordx4 v[206:209], v[46:47], off offset:384
	global_load_dwordx4 v[210:213], v[48:49], off offset:384
	global_load_dwordx4 v[220:223], v[48:49], off offset:448
	global_load_dwordx4 v[224:227], v[46:47], off offset:448
	s_waitcnt vmcnt(14)
	s_nop 1
	v_mov_b32_e32 v34, v148
	v_mov_b32_e32 v35, v149
	v_mov_b32_e32 v36, v150
	v_mov_b32_e32 v37, v151
	v_mov_b32_e32 v38, v152
	v_mov_b32_e32 v39, v153
	v_mov_b32_e32 v40, v154
	v_mov_b32_e32 v41, v155
	v_pk_fma_f32 v[2:3], v[2:3], v[36:37], v[40:41]
	v_pk_fma_f32 v[0:1], v[0:1], v[34:35], v[38:39]
	global_store_dwordx4 v[48:49], v[0:3], off
	s_waitcnt vmcnt(13)
	s_nop 1
	v_mov_b32_e32 v42, v156
	v_mov_b32_e32 v43, v157
	v_mov_b32_e32 v44, v158
	v_mov_b32_e32 v45, v159
	v_mov_b32_e32 v0, v160
	v_mov_b32_e32 v1, v161
	v_mov_b32_e32 v2, v162
	v_mov_b32_e32 v3, v163
	v_pk_fma_f32 v[2:3], v[18:19], v[2:3], v[44:45]
	v_pk_fma_f32 v[0:1], v[16:17], v[0:1], v[42:43]
	global_store_dwordx4 v[48:49], v[0:3], off offset:64
	s_waitcnt vmcnt(12)
	s_nop 1
	v_mov_b32_e32 v0, v164
	v_mov_b32_e32 v1, v165
	v_mov_b32_e32 v2, v166
	v_mov_b32_e32 v3, v167
	v_mov_b32_e32 v16, v168
	v_mov_b32_e32 v17, v169
	v_mov_b32_e32 v18, v170
	v_mov_b32_e32 v19, v171
	v_pk_fma_f32 v[2:3], v[6:7], v[2:3], v[18:19]
	v_pk_fma_f32 v[0:1], v[4:5], v[0:1], v[16:17]
	global_store_dwordx4 v[48:49], v[0:3], off offset:128
	s_waitcnt vmcnt(11)
	s_nop 1
	v_mov_b32_e32 v32, v172
	v_mov_b32_e32 v33, v173
	v_mov_b32_e32 v34, v174
	v_mov_b32_e32 v35, v175
	v_mov_b32_e32 v0, v176
	v_mov_b32_e32 v1, v177
	v_mov_b32_e32 v2, v178
	v_mov_b32_e32 v3, v179
	v_pk_fma_f32 v[2:3], v[26:27], v[2:3], v[34:35]
	v_pk_fma_f32 v[0:1], v[24:25], v[0:1], v[32:33]
	global_store_dwordx4 v[48:49], v[0:3], off offset:192
	s_waitcnt vmcnt(10)
	s_nop 1
	v_mov_b32_e32 v0, v180
	v_mov_b32_e32 v1, v181
	v_mov_b32_e32 v2, v182
	v_mov_b32_e32 v3, v183
	v_mov_b32_e32 v4, v184
	v_mov_b32_e32 v5, v185
	v_mov_b32_e32 v6, v186
	v_mov_b32_e32 v7, v187
	v_pk_fma_f32 v[2:3], v[14:15], v[2:3], v[6:7]
	v_pk_fma_f32 v[0:1], v[12:13], v[0:1], v[4:5]
	global_store_dwordx4 v[48:49], v[0:3], off offset:256
	s_waitcnt vmcnt(9)
	s_nop 1
	v_mov_b32_e32 v16, v198
	v_mov_b32_e32 v17, v199
	v_mov_b32_e32 v18, v200
	v_mov_b32_e32 v19, v201
	v_mov_b32_e32 v0, v202
	v_mov_b32_e32 v1, v203
	v_mov_b32_e32 v2, v204
	v_mov_b32_e32 v3, v205
	v_pk_fma_f32 v[2:3], v[30:31], v[2:3], v[18:19]
	v_pk_fma_f32 v[0:1], v[28:29], v[0:1], v[16:17]
	global_store_dwordx4 v[48:49], v[0:3], off offset:320
	s_waitcnt vmcnt(8)
	s_nop 1
	v_mov_b32_e32 v0, v206
	v_mov_b32_e32 v1, v207
	v_mov_b32_e32 v2, v208
	v_mov_b32_e32 v3, v209
	v_mov_b32_e32 v4, v210
	v_mov_b32_e32 v5, v211
	v_mov_b32_e32 v6, v212
	v_mov_b32_e32 v7, v213
	v_pk_fma_f32 v[2:3], v[22:23], v[2:3], v[6:7]
	v_pk_fma_f32 v[0:1], v[20:21], v[0:1], v[4:5]
	global_store_dwordx4 v[48:49], v[0:3], off offset:384
	s_waitcnt vmcnt(7)
	s_nop 1
	v_mov_b32_e32 v12, v220
	v_mov_b32_e32 v13, v221
	v_mov_b32_e32 v14, v222
	v_mov_b32_e32 v15, v223
	v_mov_b32_e32 v0, v224
	v_mov_b32_e32 v1, v225
	v_mov_b32_e32 v2, v226
	v_mov_b32_e32 v3, v227
	v_pk_fma_f32 v[2:3], v[10:11], v[2:3], v[14:15]
	v_pk_fma_f32 v[0:1], v[8:9], v[0:1], v[12:13]
	global_store_dwordx4 v[48:49], v[0:3], off offset:448
	s_cbranch_vccnz .LBB0_1841

;   DEVI void operator()(const f32x4 (&acc)[8][4], int nb, int mb, int fr, int fq, int pk) const {
;     ...
;     for (int ni = 0; ni < 4; ++ni) {
;       const int m = mb + ni * 16 + fr;
;       int bb = m / TPB, qq = m - bb * TPB;
;       float* xr = qq < CTX ? ctxres + (size_t)(bb * CTX + qq) * D : out + (size_t)(bb * SEQ + qq - CTX) * D;
;       const float* g = gate + (size_t)(qq < CTX ? 4 : bb) * MODN;
; #pragma unroll
;       for (int mi = 0; mi < 8; ++mi) {
;         const int n = nb + mi * 16 + fq * 4;
;         const f32x4 gv = *(const f32x4*)(g + n);
;         if (pk >= 0) {
;           *(f32x4*)(part + ((size_t)(pk * (NB * CTX) + bb * CTX + qq)) * D + n) = acc[mi][ni];
;         } else {
;           f32x4 xv = *(f32x4*)(xr + n);
;           xv += gv * acc[mi][ni];
;           *(f32x4*)(xr + n) = xv;
;         }
;         if ((mi & 1) == 1) asm volatile("" ::: "memory");
;       }
.LBB0_1825:
	v_add_u32_e32 v132, s63, v195
	v_mul_hi_i32 v128, v132, s55
	v_lshrrev_b32_e32 v129, 31, v128
	v_ashrrev_i32_e32 v128, 11, v128
	v_add_u32_e32 v133, v128, v129
	v_mad_i32_i24 v134, v133, s56, v132
	v_cmp_lt_i32_e32 vcc, s51, v134
	s_and_saveexec_b64 s[2:3], vcc
	s_xor_b64 s[2:3], exec, s[2:3]
	v_lshlrev_b32_e32 v128, 12, v133
	v_add3_u32 v128, v128, v134, s57
	v_ashrrev_i32_e32 v129, 31, v128
	v_lshlrev_b64 v[128:129], 13, v[128:129]
	v_lshl_add_u64 v[130:131], s[20:21], 0, v[128:129]
	v_mul_hi_i32_i24_e32 v129, 0x3000, v133
	v_mul_i32_i24_e32 v128, 0x3000, v133
	s_andn2_saveexec_b64 s[2:3], s[2:3]
	v_lshl_add_u32 v128, v133, 8, v134
	v_ashrrev_i32_e32 v129, 31, v128
	v_lshlrev_b64 v[128:129], 13, v[128:129]
	v_lshl_add_u64 v[130:131], s[4:5], 0, v[128:129]
	v_mov_b64_e32 v[128:129], 0xc000
	s_or_b64 exec, exec, s[2:3]
	v_add_u32_e32 v134, s62, v196
	v_ashrrev_i32_e32 v135, 31, v134
	v_lshl_add_u64 v[136:137], v[128:129], 2, s[6:7]
	v_lshlrev_b64 v[128:129], 2, v[134:135]
	v_lshl_add_u64 v[146:147], v[136:137], 0, v[128:129]
	v_lshl_add_u64 v[130:131], v[130:131], 0, v[128:129]
	global_load_dwordx4 v[148:151], v[146:147], off
	global_load_dwordx4 v[152:155], v[130:131], off
	global_load_dwordx4 v[156:159], v[130:131], off offset:64
	global_load_dwordx4 v[160:163], v[146:147], off offset:64
	global_load_dwordx4 v[164:167], v[146:147], off offset:128
	global_load_dwordx4 v[168:171], v[130:131], off offset:128
	global_load_dwordx4 v[172:175], v[130:131], off offset:192
	global_load_dwordx4 v[176:179], v[146:147], off offset:192
	global_load_dwordx4 v[180:183], v[146:147], off offset:256
	global_load_dwordx4 v[184:187], v[130:131], off offset:256
	global_load_dwordx4 v[198:201], v[130:131], off offset:320
	global_load_dwordx4 v[202:205], v[146:147], off offset:320
	global_load_dwordx4 v[206:209], v[146:147], off offset:384
	global_load_dwordx4 v[210:213], v[130:131], off offset:384
	global_load_dwordx4 v[220:223], v[130:131], off offset:448
	global_load_dwordx4 v[224:227], v[146:147], off offset:448
	s_waitcnt vmcnt(14)
	s_nop 1
	v_mov_b32_e32 v134, v148
	v_mov_b32_e32 v135, v149
	v_mov_b32_e32 v136, v150
	v_mov_b32_e32 v137, v151
	v_mov_b32_e32 v138, v152
	v_mov_b32_e32 v139, v153
	v_mov_b32_e32 v140, v154
	v_mov_b32_e32 v141, v155
	v_pk_fma_f32 v[98:99], v[98:99], v[136:137], v[140:141]
	v_pk_fma_f32 v[96:97], v[96:97], v[134:135], v[138:139]
	global_store_dwordx4 v[130:131], v[96:99], off
	s_waitcnt vmcnt(13)
	s_nop 1
	v_mov_b32_e32 v142, v156
	v_mov_b32_e32 v143, v157
	v_mov_b32_e32 v144, v158
	v_mov_b32_e32 v145, v159
	v_mov_b32_e32 v96, v160
	v_mov_b32_e32 v97, v161
	v_mov_b32_e32 v98, v162
	v_mov_b32_e32 v99, v163
	v_pk_fma_f32 v[98:99], v[114:115], v[98:99], v[144:145]
	v_pk_fma_f32 v[96:97], v[112:113], v[96:97], v[142:143]
	global_store_dwordx4 v[130:131], v[96:99], off offset:64
	s_waitcnt vmcnt(12)
	s_nop 1
	v_mov_b32_e32 v96, v164
	v_mov_b32_e32 v97, v165
	v_mov_b32_e32 v98, v166
	v_mov_b32_e32 v99, v167
	v_mov_b32_e32 v112, v168
	v_mov_b32_e32 v113, v169
	v_mov_b32_e32 v114, v170
	v_mov_b32_e32 v115, v171
	v_pk_fma_f32 v[98:99], v[102:103], v[98:99], v[114:115]
	v_pk_fma_f32 v[96:97], v[100:101], v[96:97], v[112:113]
	global_store_dwordx4 v[130:131], v[96:99], off offset:128
	s_waitcnt vmcnt(11)
	s_nop 1
	v_mov_b32_e32 v134, v172
	v_mov_b32_e32 v135, v173
	v_mov_b32_e32 v136, v174
	v_mov_b32_e32 v137, v175
	v_mov_b32_e32 v96, v176
	v_mov_b32_e32 v97, v177
	v_mov_b32_e32 v98, v178
	v_mov_b32_e32 v99, v179
	v_pk_fma_f32 v[98:99], v[122:123], v[98:99], v[136:137]
	v_pk_fma_f32 v[96:97], v[120:121], v[96:97], v[134:135]
	global_store_dwordx4 v[130:131], v[96:99], off offset:192
	s_waitcnt vmcnt(10)
	s_nop 1
	v_mov_b32_e32 v96, v180
	v_mov_b32_e32 v97, v181
	v_mov_b32_e32 v98, v182
	v_mov_b32_e32 v99, v183
	v_mov_b32_e32 v100, v184
	v_mov_b32_e32 v101, v185
	v_mov_b32_e32 v102, v186
	v_mov_b32_e32 v103, v187
	v_pk_fma_f32 v[98:99], v[106:107], v[98:99], v[102:103]
	v_pk_fma_f32 v[96:97], v[104:105], v[96:97], v[100:101]
	global_store_dwordx4 v[130:131], v[96:99], off offset:256
	s_waitcnt vmcnt(9)
	s_nop 1
	v_mov_b32_e32 v112, v198
	v_mov_b32_e32 v113, v199
	v_mov_b32_e32 v114, v200
	v_mov_b32_e32 v115, v201
	v_mov_b32_e32 v96, v202
	v_mov_b32_e32 v97, v203
	v_mov_b32_e32 v98, v204
	v_mov_b32_e32 v99, v205
	v_pk_fma_f32 v[98:99], v[126:127], v[98:99], v[114:115]
	v_pk_fma_f32 v[96:97], v[124:125], v[96:97], v[112:113]
	global_store_dwordx4 v[130:131], v[96:99], off offset:320
	s_waitcnt vmcnt(8)
	s_nop 1
	v_mov_b32_e32 v96, v206
	v_mov_b32_e32 v97, v207
	v_mov_b32_e32 v98, v208
	v_mov_b32_e32 v99, v209
	v_mov_b32_e32 v100, v210
	v_mov_b32_e32 v101, v211
	v_mov_b32_e32 v102, v212
	v_mov_b32_e32 v103, v213
	v_pk_fma_f32 v[98:99], v[118:119], v[98:99], v[102:103]
	v_pk_fma_f32 v[96:97], v[116:117], v[96:97], v[100:101]
	global_store_dwordx4 v[130:131], v[96:99], off offset:384
	v_add_u32_e32 v101, 16, v132
	v_mul_hi_i32 v100, v101, s55
	v_lshrrev_b32_e32 v102, 31, v100
	s_waitcnt vmcnt(7)
;   DEVI void operator()(const f32x4 (&acc)[8][4], int nb, int mb, int fr, int fq, int pk) const {
;     ...
;     for (int ni = 0; ni < 4; ++ni) {
;       const int m = mb + ni * 16 + fr;
;       int bb = m / TPB, qq = m - bb * TPB;
;       float* xr = qq < CTX ? ctxres + (size_t)(bb * CTX + qq) * D : out + (size_t)(bb * SEQ + qq - CTX) * D;
;       const float* g = gate + (size_t)(qq < CTX ? 4 : bb) * MODN;
; #pragma unroll
;       for (int mi = 0; mi < 8; ++mi) {
;         const int n = nb + mi * 16 + fq * 4;
;         const f32x4 gv = *(const f32x4*)(g + n);
;         if (pk >= 0) {
;           *(f32x4*)(part + ((size_t)(pk * (NB * CTX) + bb * CTX + qq)) * D + n) = acc[mi][ni];
;         } else {
;           f32x4 xv = *(f32x4*)(xr + n);
;           xv += gv * acc[mi][ni];
;           *(f32x4*)(xr + n) = xv;
;         }
;         if ((mi & 1) == 1) asm volatile("" ::: "memory");
;       }
	s_nop 1
	v_mov_b32_e32 v104, v220
	v_mov_b32_e32 v105, v221
	v_mov_b32_e32 v106, v222
	v_mov_b32_e32 v107, v223
	v_mov_b32_e32 v96, v224
	v_mov_b32_e32 v97, v225
	v_mov_b32_e32 v98, v226
	v_mov_b32_e32 v99, v227
	v_pk_fma_f32 v[98:99], v[110:111], v[98:99], v[106:107]
	v_pk_fma_f32 v[96:97], v[108:109], v[96:97], v[104:105]
	global_store_dwordx4 v[130:131], v[96:99], off offset:448
	s_nop 1
	v_ashrrev_i32_e32 v96, 11, v100
	v_add_u32_e32 v100, v96, v102
	v_mad_i32_i24 v101, v100, s56, v101
	v_cmp_lt_i32_e32 vcc, s51, v101
	s_and_saveexec_b64 s[2:3], vcc
	s_xor_b64 s[2:3], exec, s[2:3]
	v_lshlrev_b32_e32 v96, 12, v100
	v_add3_u32 v96, v96, v101, s57
	v_ashrrev_i32_e32 v97, 31, v96
	v_lshlrev_b64 v[96:97], 13, v[96:97]
	v_lshl_add_u64 v[96:97], s[20:21], 0, v[96:97]
	v_mul_hi_i32_i24_e32 v99, 0x3000, v100
	v_mul_i32_i24_e32 v98, 0x3000, v100
	s_andn2_saveexec_b64 s[2:3], s[2:3]
	v_lshl_add_u32 v96, v100, 8, v101
	v_ashrrev_i32_e32 v97, 31, v96
	v_lshlrev_b64 v[96:97], 13, v[96:97]
	v_lshl_add_u64 v[96:97], s[4:5], 0, v[96:97]
	v_mov_b64_e32 v[98:99], 0xc000
	s_or_b64 exec, exec, s[2:3]
	v_lshl_add_u64 v[98:99], v[98:99], 2, s[6:7]
	v_lshl_add_u64 v[110:111], v[98:99], 0, v[128:129]
	v_lshl_add_u64 v[112:113], v[96:97], 0, v[128:129]
	global_load_dwordx4 v[148:151], v[110:111], off
	global_load_dwordx4 v[152:155], v[112:113], off
	global_load_dwordx4 v[156:159], v[112:113], off offset:64
	global_load_dwordx4 v[160:163], v[110:111], off offset:64
	global_load_dwordx4 v[164:167], v[110:111], off offset:128
	global_load_dwordx4 v[168:171], v[112:113], off offset:128
	global_load_dwordx4 v[172:175], v[112:113], off offset:192
	global_load_dwordx4 v[176:179], v[110:111], off offset:192
	global_load_dwordx4 v[180:183], v[110:111], off offset:256
	global_load_dwordx4 v[184:187], v[112:113], off offset:256
	global_load_dwordx4 v[198:201], v[112:113], off offset:320
	global_load_dwordx4 v[202:205], v[110:111], off offset:320
	global_load_dwordx4 v[206:209], v[110:111], off offset:384
	global_load_dwordx4 v[210:213], v[112:113], off offset:384
	global_load_dwordx4 v[220:223], v[112:113], off offset:448
	global_load_dwordx4 v[224:227], v[110:111], off offset:448
	s_waitcnt vmcnt(14)
	s_nop 1
	v_mov_b32_e32 v98, v148
	v_mov_b32_e32 v99, v149
	v_mov_b32_e32 v100, v150
	v_mov_b32_e32 v101, v151
	v_mov_b32_e32 v102, v152
	v_mov_b32_e32 v103, v153
	v_mov_b32_e32 v104, v154
	v_mov_b32_e32 v105, v155
	v_pk_fma_f32 v[66:67], v[66:67], v[100:101], v[104:105]
	v_pk_fma_f32 v[64:65], v[64:65], v[98:99], v[102:103]
	global_store_dwordx4 v[112:113], v[64:67], off
	s_waitcnt vmcnt(13)
	s_nop 1
	v_mov_b32_e32 v106, v156
	v_mov_b32_e32 v107, v157
	v_mov_b32_e32 v108, v158
	v_mov_b32_e32 v109, v159
	v_mov_b32_e32 v64, v160
	v_mov_b32_e32 v65, v161
	v_mov_b32_e32 v66, v162
	v_mov_b32_e32 v67, v163
	v_pk_fma_f32 v[66:67], v[82:83], v[66:67], v[108:109]
	v_pk_fma_f32 v[64:65], v[80:81], v[64:65], v[106:107]
	global_store_dwordx4 v[112:113], v[64:67], off offset:64
	s_waitcnt vmcnt(12)
	s_nop 1
	v_mov_b32_e32 v64, v164
	v_mov_b32_e32 v65, v165
	v_mov_b32_e32 v66, v166
	v_mov_b32_e32 v67, v167
	v_mov_b32_e32 v80, v168
	v_mov_b32_e32 v81, v169
	v_mov_b32_e32 v82, v170
	v_mov_b32_e32 v83, v171
	v_pk_fma_f32 v[66:67], v[70:71], v[66:67], v[82:83]
	v_pk_fma_f32 v[64:65], v[68:69], v[64:65], v[80:81]
	global_store_dwordx4 v[112:113], v[64:67], off offset:128
	s_waitcnt vmcnt(11)
	s_nop 1
	v_mov_b32_e32 v96, v172
	v_mov_b32_e32 v97, v173
	v_mov_b32_e32 v98, v174
	v_mov_b32_e32 v99, v175
	v_mov_b32_e32 v64, v176
	v_mov_b32_e32 v65, v177
	v_mov_b32_e32 v66, v178
	v_mov_b32_e32 v67, v179
	v_pk_fma_f32 v[66:67], v[90:91], v[66:67], v[98:99]
	v_pk_fma_f32 v[64:65], v[88:89], v[64:65], v[96:97]
	global_store_dwordx4 v[112:113], v[64:67], off offset:192
	s_waitcnt vmcnt(10)
	s_nop 1
	v_mov_b32_e32 v64, v180
	v_mov_b32_e32 v65, v181
	v_mov_b32_e32 v66, v182
	v_mov_b32_e32 v67, v183
	v_mov_b32_e32 v68, v184
	v_mov_b32_e32 v69, v185
	v_mov_b32_e32 v70, v186
	v_mov_b32_e32 v71, v187
	v_pk_fma_f32 v[66:67], v[74:75], v[66:67], v[70:71]
	v_pk_fma_f32 v[64:65], v[72:73], v[64:65], v[68:69]
	global_store_dwordx4 v[112:113], v[64:67], off offset:256
	s_waitcnt vmcnt(9)
	s_nop 1
	v_mov_b32_e32 v80, v198
	v_mov_b32_e32 v81, v199
	v_mov_b32_e32 v82, v200
	v_mov_b32_e32 v83, v201
	v_mov_b32_e32 v64, v202
	v_mov_b32_e32 v65, v203
	v_mov_b32_e32 v66, v204
	v_mov_b32_e32 v67, v205
	v_pk_fma_f32 v[66:67], v[94:95], v[66:67], v[82:83]
	v_pk_fma_f32 v[64:65], v[92:93], v[64:65], v[80:81]
	global_store_dwordx4 v[112:113], v[64:67], off offset:320
	s_waitcnt vmcnt(8)
	s_nop 1
	v_mov_b32_e32 v64, v206
	v_mov_b32_e32 v65, v207
	v_mov_b32_e32 v66, v208
	v_mov_b32_e32 v67, v209
	v_mov_b32_e32 v68, v210
	v_mov_b32_e32 v69, v211
	v_mov_b32_e32 v70, v212
	v_mov_b32_e32 v71, v213
	v_pk_fma_f32 v[66:67], v[86:87], v[66:67], v[70:71]
	v_pk_fma_f32 v[64:65], v[84:85], v[64:65], v[68:69]
	global_store_dwordx4 v[112:113], v[64:67], off offset:384
	v_add_u32_e32 v69, 32, v132
	v_mul_hi_i32 v68, v69, s55
	v_lshrrev_b32_e32 v70, 31, v68
	s_waitcnt vmcnt(7)
;   DEVI void operator()(const f32x4 (&acc)[8][4], int nb, int mb, int fr, int fq, int pk) const {
;     ...
;     for (int ni = 0; ni < 4; ++ni) {
;       const int m = mb + ni * 16 + fr;
;       int bb = m / TPB, qq = m - bb * TPB;
;       float* xr = qq < CTX ? ctxres + (size_t)(bb * CTX + qq) * D : out + (size_t)(bb * SEQ + qq - CTX) * D;
;       const float* g = gate + (size_t)(qq < CTX ? 4 : bb) * MODN;
; #pragma unroll
;       for (int mi = 0; mi < 8; ++mi) {
;         const int n = nb + mi * 16 + fq * 4;
;         const f32x4 gv = *(const f32x4*)(g + n);
;         if (pk >= 0) {
;           *(f32x4*)(part + ((size_t)(pk * (NB * CTX) + bb * CTX + qq)) * D + n) = acc[mi][ni];
;         } else {
;           f32x4 xv = *(f32x4*)(xr + n);
;           xv += gv * acc[mi][ni];
;           *(f32x4*)(xr + n) = xv;
;         }
;         if ((mi & 1) == 1) asm volatile("" ::: "memory");
;       }
	s_nop 1
	v_mov_b32_e32 v72, v220
	v_mov_b32_e32 v73, v221
	v_mov_b32_e32 v74, v222
	v_mov_b32_e32 v75, v223
	v_mov_b32_e32 v64, v224
	v_mov_b32_e32 v65, v225
	v_mov_b32_e32 v66, v226
	v_mov_b32_e32 v67, v227
	v_pk_fma_f32 v[66:67], v[78:79], v[66:67], v[74:75]
	v_pk_fma_f32 v[64:65], v[76:77], v[64:65], v[72:73]
	global_store_dwordx4 v[112:113], v[64:67], off offset:448
	s_nop 1
	v_ashrrev_i32_e32 v64, 11, v68
	v_add_u32_e32 v68, v64, v70
	v_mad_i32_i24 v69, v68, s56, v69
	v_cmp_lt_i32_e32 vcc, s51, v69
	s_and_saveexec_b64 s[2:3], vcc
	s_xor_b64 s[2:3], exec, s[2:3]
	v_lshlrev_b32_e32 v64, 12, v68
	v_add3_u32 v64, v64, v69, s57
	v_ashrrev_i32_e32 v65, 31, v64
	v_lshlrev_b64 v[64:65], 13, v[64:65]
	v_lshl_add_u64 v[64:65], s[20:21], 0, v[64:65]
	v_mul_hi_i32_i24_e32 v67, 0x3000, v68
	v_mul_i32_i24_e32 v66, 0x3000, v68
	s_andn2_saveexec_b64 s[2:3], s[2:3]
	v_lshl_add_u32 v64, v68, 8, v69
	v_ashrrev_i32_e32 v65, 31, v64
	v_lshlrev_b64 v[64:65], 13, v[64:65]
	v_lshl_add_u64 v[64:65], s[4:5], 0, v[64:65]
	v_mov_b64_e32 v[66:67], 0xc000
	s_or_b64 exec, exec, s[2:3]
	v_lshl_add_u64 v[66:67], v[66:67], 2, s[6:7]
	v_lshl_add_u64 v[78:79], v[66:67], 0, v[128:129]
	v_lshl_add_u64 v[80:81], v[64:65], 0, v[128:129]
	global_load_dwordx4 v[148:151], v[78:79], off
	global_load_dwordx4 v[152:155], v[80:81], off
	global_load_dwordx4 v[156:159], v[80:81], off offset:64
	global_load_dwordx4 v[160:163], v[78:79], off offset:64
	global_load_dwordx4 v[164:167], v[78:79], off offset:128
	global_load_dwordx4 v[168:171], v[80:81], off offset:128
	global_load_dwordx4 v[172:175], v[80:81], off offset:192
	global_load_dwordx4 v[176:179], v[78:79], off offset:192
	global_load_dwordx4 v[180:183], v[78:79], off offset:256
	global_load_dwordx4 v[184:187], v[80:81], off offset:256
	global_load_dwordx4 v[198:201], v[80:81], off offset:320
	global_load_dwordx4 v[202:205], v[78:79], off offset:320
	global_load_dwordx4 v[206:209], v[78:79], off offset:384
	global_load_dwordx4 v[210:213], v[80:81], off offset:384
	global_load_dwordx4 v[220:223], v[80:81], off offset:448
	global_load_dwordx4 v[224:227], v[78:79], off offset:448
	s_waitcnt vmcnt(14)
	s_nop 1
	v_mov_b32_e32 v66, v148
	v_mov_b32_e32 v67, v149
	v_mov_b32_e32 v68, v150
	v_mov_b32_e32 v69, v151
	v_mov_b32_e32 v70, v152
	v_mov_b32_e32 v71, v153
	v_mov_b32_e32 v72, v154
	v_mov_b32_e32 v73, v155
	v_pk_fma_f32 v[34:35], v[34:35], v[68:69], v[72:73]
	v_pk_fma_f32 v[32:33], v[32:33], v[66:67], v[70:71]
	global_store_dwordx4 v[80:81], v[32:35], off
	s_waitcnt vmcnt(13)
	s_nop 1
	v_mov_b32_e32 v74, v156
	v_mov_b32_e32 v75, v157
	v_mov_b32_e32 v76, v158
	v_mov_b32_e32 v77, v159
	v_mov_b32_e32 v32, v160
	v_mov_b32_e32 v33, v161
	v_mov_b32_e32 v34, v162
	v_mov_b32_e32 v35, v163
	v_pk_fma_f32 v[34:35], v[50:51], v[34:35], v[76:77]
	v_pk_fma_f32 v[32:33], v[48:49], v[32:33], v[74:75]
	global_store_dwordx4 v[80:81], v[32:35], off offset:64
	s_waitcnt vmcnt(12)
	s_nop 1
	v_mov_b32_e32 v32, v164
	v_mov_b32_e32 v33, v165
	v_mov_b32_e32 v34, v166
	v_mov_b32_e32 v35, v167
	v_mov_b32_e32 v48, v168
	v_mov_b32_e32 v49, v169
	v_mov_b32_e32 v50, v170
	v_mov_b32_e32 v51, v171
	v_pk_fma_f32 v[34:35], v[38:39], v[34:35], v[50:51]
	v_pk_fma_f32 v[32:33], v[36:37], v[32:33], v[48:49]
	global_store_dwordx4 v[80:81], v[32:35], off offset:128
	s_waitcnt vmcnt(11)
	s_nop 1
	v_mov_b32_e32 v64, v172
	v_mov_b32_e32 v65, v173
	v_mov_b32_e32 v66, v174
	v_mov_b32_e32 v67, v175
	v_mov_b32_e32 v32, v176
	v_mov_b32_e32 v33, v177
	v_mov_b32_e32 v34, v178
	v_mov_b32_e32 v35, v179
	v_pk_fma_f32 v[34:35], v[58:59], v[34:35], v[66:67]
	v_pk_fma_f32 v[32:33], v[56:57], v[32:33], v[64:65]
	global_store_dwordx4 v[80:81], v[32:35], off offset:192
	s_waitcnt vmcnt(10)
	s_nop 1
	v_mov_b32_e32 v32, v180
	v_mov_b32_e32 v33, v181
	v_mov_b32_e32 v34, v182
	v_mov_b32_e32 v35, v183
	v_mov_b32_e32 v36, v184
	v_mov_b32_e32 v37, v185
	v_mov_b32_e32 v38, v186
	v_mov_b32_e32 v39, v187
	v_pk_fma_f32 v[34:35], v[42:43], v[34:35], v[38:39]
	v_pk_fma_f32 v[32:33], v[40:41], v[32:33], v[36:37]
	global_store_dwordx4 v[80:81], v[32:35], off offset:256
	s_waitcnt vmcnt(9)
	s_nop 1
	v_mov_b32_e32 v48, v198
	v_mov_b32_e32 v49, v199
	v_mov_b32_e32 v50, v200
	v_mov_b32_e32 v51, v201
	v_mov_b32_e32 v32, v202
	v_mov_b32_e32 v33, v203
	v_mov_b32_e32 v34, v204
	v_mov_b32_e32 v35, v205
	v_pk_fma_f32 v[34:35], v[62:63], v[34:35], v[50:51]
	v_pk_fma_f32 v[32:33], v[60:61], v[32:33], v[48:49]
	global_store_dwordx4 v[80:81], v[32:35], off offset:320
	s_waitcnt vmcnt(8)
	s_nop 1
	v_mov_b32_e32 v32, v206
	v_mov_b32_e32 v33, v207
	v_mov_b32_e32 v34, v208
	v_mov_b32_e32 v35, v209
	v_mov_b32_e32 v36, v210
	v_mov_b32_e32 v37, v211
	v_mov_b32_e32 v38, v212
	v_mov_b32_e32 v39, v213
	v_pk_fma_f32 v[34:35], v[54:55], v[34:35], v[38:39]
	v_pk_fma_f32 v[32:33], v[52:53], v[32:33], v[36:37]
	global_store_dwordx4 v[80:81], v[32:35], off offset:384
	v_add_u32_e32 v37, 48, v132
	v_mul_hi_i32 v36, v37, s55
	v_lshrrev_b32_e32 v38, 31, v36
	s_waitcnt vmcnt(7)
	s_nop 1
	v_mov_b32_e32 v40, v220
	v_mov_b32_e32 v41, v221
	v_mov_b32_e32 v42, v222
	v_mov_b32_e32 v43, v223
	v_mov_b32_e32 v32, v224
	v_mov_b32_e32 v33, v225
	v_mov_b32_e32 v34, v226
	v_mov_b32_e32 v35, v227
	v_pk_fma_f32 v[34:35], v[46:47], v[34:35], v[42:43]
	v_pk_fma_f32 v[32:33], v[44:45], v[32:33], v[40:41]
	global_store_dwordx4 v[80:81], v[32:35], off offset:448
	s_nop 1
	v_ashrrev_i32_e32 v32, 11, v36
	v_add_u32_e32 v36, v32, v38
	v_mad_i32_i24 v37, v36, s56, v37
	v_cmp_lt_i32_e32 vcc, s51, v37
	s_and_saveexec_b64 s[2:3], vcc
	s_xor_b64 s[2:3], exec, s[2:3]
	v_lshlrev_b32_e32 v32, 12, v36
	v_add3_u32 v32, v32, v37, s57
	v_ashrrev_i32_e32 v33, 31, v32
	v_lshlrev_b64 v[32:33], 13, v[32:33]
	v_lshl_add_u64 v[32:33], s[20:21], 0, v[32:33]
	v_mul_hi_i32_i24_e32 v35, 0x3000, v36
	v_mul_i32_i24_e32 v34, 0x3000, v36
	s_andn2_saveexec_b64 s[2:3], s[2:3]
	s_cbranch_execz .LBB0_1791
	v_lshl_add_u32 v32, v36, 8, v37
	v_ashrrev_i32_e32 v33, 31, v32
	v_lshlrev_b64 v[32:33], 13, v[32:33]
	v_lshl_add_u64 v[32:33], s[4:5], 0, v[32:33]
	v_mov_b64_e32 v[34:35], 0xc000
	s_branch .LBB0_1791
